# K loops: s_setprio 1 raised before the opening barrier, s_setprio 0 after the closing barrier, redundant post-barrier lgkmcnt(0) and mid-block flip pair removed
# speedup vs baseline: 1.0059x; 1.0059x over previous
; #define PG8_STAGE(bufoff, gbase, voff) do { _Pragma("unroll") for (int _i = 0; _i < 2; ++_i) \
;         __builtin_amdgcn_global_load_lds((const unsigned*)((const char*)(gbase) + (voff)[_i]), (PG8_LAS unsigned*)(lds + (bufoff) + ldsw + _i * 8192), 16, 0, 0); } while (0)
; #define PG8_LDA(dst, b, h) do { _Pragma("unroll") for (int m = 0; m < 4; ++m) _Pragma("unroll") for (int k = 0; k < 2; ++k) dst[m][k] = *(const PG8_LAS bf16x8*)(lds + PG8_SA(b, h) + aoff + m * 2048 + k * 1024); } while (0)
; #define PG8_LDB(dst, b, h) do { _Pragma("unroll") for (int n = 0; n < 2; ++n) _Pragma("unroll") for (int k = 0; k < 2; ++k) dst[n][k] = *(const PG8_LAS bf16x8*)(lds + PG8_SB(b, h) + boff + n * 2048 + k * 1024); } while (0)
; #define PG8_MMA(ai, bj, At, Bt) do { __builtin_amdgcn_s_setprio(1); _Pragma("unroll") for (int m = 0; m < 4; ++m) _Pragma("unroll") for (int n = 0; n < 2; ++n) _Pragma("unroll") for (int k = 0; k < 2; ++k) \
;         acc[ai][bj][m][n] = __builtin_amdgcn_mfma_f32_16x16x32_bf16(Bt[n][k], At[m][k], acc[ai][bj][m][n], 0, 0, 0); __builtin_amdgcn_s_setprio(0); } while (0)
; #define PG8_WAIT_V(n) asm volatile("s_waitcnt vmcnt(" #n ")" ::: "memory")
; #define PG8_WAIT_L(n) asm volatile("s_waitcnt lgkmcnt(" #n ")" ::: "memory")
; #define PG8_BAR __builtin_amdgcn_s_barrier()
; #define PG8_SCHED __builtin_amdgcn_sched_barrier(0)
; template <class Epi, class Sched, bool ALIGN_EPI = false, bool SP2 = false>
; __device__ __forceinline__ void gemm_phase(PG8_LAS unsigned char* lds, const Gemm g, const Sched& S, const Epi& E) {
;     ...
;             const bool last = (t == nt - 2);
;             const char* a1 = cA + (size_t)(t + 1) * kstep;
;             const char* a2 = last ? nA : cA + (size_t)(t + 2) * kstep; const char* b2 = last ? nB : cB + (size_t)(t + 2) * kstep;
;             const char* a3 = a2 + kstep; const char* b3 = b2 + kstep;
;             if (last && has_next) S.a_ready(nxt);
;             if constexpr (SP2) {
;             PG8_LDB(B0, 0, 0); PG8_LDB(B1, 0, 1); PG8_SCHED; PG8_LDA(At, 0, 0); PG8_STAGE(PG8_SA(1, 1), a1 + hstep, voffA);
;             PG8_WAIT_V(8); PG8_WAIT_L(0); PG8_BAR; PG8_MMA(0, 0, At, B0); PG8_MMA(0, 1, At, B1); PG8_BAR; PG8_SCHED;
;             PG8_LDA(At, 0, 1); PG8_STAGE(PG8_SB(0, 0), b2, voffB); PG8_STAGE(PG8_SB(0, 1), b2 + hstep, voffB); PG8_STAGE(PG8_SA(0, 0), a2, voffA);
.LBB0_165:
	s_add_u32 s68, s42, 0xfff80080
	s_addc_u32 s69, s43, -1
	s_add_i32 s82, 0, 0x10000
	s_cmp_eq_u32 s71, 28
	s_cselect_b32 s81, s47, s69
	s_cselect_b32 s80, s55, s68
	v_add_u32_e32 v144, s82, v147
	s_cselect_b32 s79, s45, s63
	s_cselect_b32 s78, s58, s59
	s_add_i32 s83, 0, 0x14000
	ds_read_b128 v[140:143], v144
	ds_read_b128 v[156:159], v144 offset:1024
	ds_read_b128 v[160:163], v144 offset:2048
	ds_read_b128 v[164:167], v144 offset:3072
	v_add_u32_e32 v144, s83, v147
	ds_read_b128 v[168:171], v144
	ds_read_b128 v[172:175], v144 offset:1024
	ds_read_b128 v[192:195], v144 offset:2048
	ds_read_b128 v[196:199], v144 offset:3072
	v_lshl_add_u64 v[150:151], s[42:43], 0, v[136:137]
	s_add_i32 m0, s14, 0xc000
	ds_read_b128 v[200:203], v149
	ds_read_b128 v[204:207], v149 offset:1024
	ds_read_b128 v[208:211], v149 offset:2048
	ds_read_b128 v[212:215], v149 offset:3072
	ds_read_b128 v[216:219], v149 offset:4096
	ds_read_b128 v[220:223], v149 offset:5120
	ds_read_b128 v[224:227], v149 offset:6144
	ds_read_b128 v[228:231], v149 offset:7168
	global_load_lds_dwordx4 v[150:151], off
	v_lshl_add_u64 v[150:151], s[42:43], 0, v[138:139]
	s_add_i32 m0, s14, 0xe000
	s_nop 0
	global_load_lds_dwordx4 v[150:151], off
	s_waitcnt vmcnt(8)
	s_waitcnt lgkmcnt(0)
	s_setprio 1
	s_barrier
	v_mfma_f32_16x16x32_bf16 v[124:127], v[140:143], v[200:203], v[124:127]
	v_mfma_f32_16x16x32_bf16 v[120:123], v[160:163], v[200:203], v[120:123]
	v_mfma_f32_16x16x32_bf16 v[108:111], v[140:143], v[208:211], v[108:111]
	v_mfma_f32_16x16x32_bf16 v[104:107], v[160:163], v[208:211], v[104:107]
	v_mfma_f32_16x16x32_bf16 v[92:95], v[140:143], v[216:219], v[92:95]
	v_mfma_f32_16x16x32_bf16 v[88:91], v[160:163], v[216:219], v[88:91]
	v_mfma_f32_16x16x32_bf16 v[76:79], v[140:143], v[224:227], v[76:79]
	v_mfma_f32_16x16x32_bf16 v[72:75], v[160:163], v[224:227], v[72:75]
	v_mfma_f32_16x16x32_bf16 v[124:127], v[156:159], v[204:207], v[124:127]
	v_mfma_f32_16x16x32_bf16 v[120:123], v[164:167], v[204:207], v[120:123]
	v_mfma_f32_16x16x32_bf16 v[108:111], v[156:159], v[212:215], v[108:111]
	v_mfma_f32_16x16x32_bf16 v[104:107], v[164:167], v[212:215], v[104:107]
	v_mfma_f32_16x16x32_bf16 v[92:95], v[156:159], v[220:223], v[92:95]
	v_mfma_f32_16x16x32_bf16 v[88:91], v[164:167], v[220:223], v[88:91]
	v_mfma_f32_16x16x32_bf16 v[76:79], v[156:159], v[228:231], v[76:79]
	v_mfma_f32_16x16x32_bf16 v[72:75], v[164:167], v[228:231], v[72:75]
	v_mfma_f32_16x16x32_bf16 v[116:119], v[168:171], v[200:203], v[116:119]
	v_mfma_f32_16x16x32_bf16 v[112:115], v[192:195], v[200:203], v[112:115]
	v_mfma_f32_16x16x32_bf16 v[100:103], v[168:171], v[208:211], v[100:103]
	v_mfma_f32_16x16x32_bf16 v[96:99], v[192:195], v[208:211], v[96:99]
	v_mfma_f32_16x16x32_bf16 v[84:87], v[168:171], v[216:219], v[84:87]
	v_mfma_f32_16x16x32_bf16 v[80:83], v[192:195], v[216:219], v[80:83]
	v_mfma_f32_16x16x32_bf16 v[68:71], v[168:171], v[224:227], v[68:71]
	v_mfma_f32_16x16x32_bf16 v[64:67], v[192:195], v[224:227], v[64:67]
	v_mfma_f32_16x16x32_bf16 v[116:119], v[172:175], v[204:207], v[116:119]
	v_mfma_f32_16x16x32_bf16 v[112:115], v[196:199], v[204:207], v[112:115]
	v_mfma_f32_16x16x32_bf16 v[100:103], v[172:175], v[212:215], v[100:103]
	v_mfma_f32_16x16x32_bf16 v[96:99], v[196:199], v[212:215], v[96:99]
	v_mfma_f32_16x16x32_bf16 v[84:87], v[172:175], v[220:223], v[84:87]
	v_mfma_f32_16x16x32_bf16 v[80:83], v[196:199], v[220:223], v[80:83]
	v_mfma_f32_16x16x32_bf16 v[68:71], v[172:175], v[228:231], v[68:71]
	v_mfma_f32_16x16x32_bf16 v[64:67], v[196:199], v[228:231], v[64:67]
	s_barrier
	s_setprio 0
	s_add_i32 s68, s82, s0
	v_lshl_add_u64 v[150:151], s[78:79], 0, v[152:153]
	s_mov_b32 m0, s68
	ds_read_b128 v[200:203], v149 offset:16384
	ds_read_b128 v[204:207], v149 offset:17408
	ds_read_b128 v[208:211], v149 offset:18432
	ds_read_b128 v[212:215], v149 offset:19456
	ds_read_b128 v[216:219], v149 offset:20480
	ds_read_b128 v[220:223], v149 offset:21504
	ds_read_b128 v[224:227], v149 offset:22528
	ds_read_b128 v[228:231], v149 offset:23552
	global_load_lds_dwordx4 v[150:151], off
	s_add_i32 m0, s68, 0x2000
	s_add_u32 s68, s78, 0x80000
	v_lshl_add_u64 v[182:183], s[78:79], 0, v[128:129]
	s_addc_u32 s69, s79, 0
	s_add_i32 s82, s83, s0
	global_load_lds_dwordx4 v[182:183], off
	v_lshl_add_u64 v[184:185], s[68:69], 0, v[152:153]
	s_mov_b32 m0, s82
	v_lshl_add_u64 v[188:189], s[80:81], 0, v[130:131]
	global_load_lds_dwordx4 v[184:185], off
	v_lshl_add_u64 v[184:185], s[68:69], 0, v[128:129]
	s_add_i32 m0, s82, 0x2000
	s_nop 0
	global_load_lds_dwordx4 v[184:185], off
	v_lshl_add_u64 v[184:185], s[80:81], 0, v[132:133]
	s_mov_b32 m0, s14
	s_nop 0
	global_load_lds_dwordx4 v[184:185], off
	s_mov_b32 m0, s15
	s_nop 0
	global_load_lds_dwordx4 v[188:189], off
	s_waitcnt vmcnt(8)
	s_waitcnt lgkmcnt(0)
	s_setprio 1
	s_barrier
; #define PG8_STAGE(bufoff, gbase, voff) do { _Pragma("unroll") for (int _i = 0; _i < 2; ++_i) \
;         __builtin_amdgcn_global_load_lds((const unsigned*)((const char*)(gbase) + (voff)[_i]), (PG8_LAS unsigned*)(lds + (bufoff) + ldsw + _i * 8192), 16, 0, 0); } while (0)
; #define PG8_LDA(dst, b, h) do { _Pragma("unroll") for (int m = 0; m < 4; ++m) _Pragma("unroll") for (int k = 0; k < 2; ++k) dst[m][k] = *(const PG8_LAS bf16x8*)(lds + PG8_SA(b, h) + aoff + m * 2048 + k * 1024); } while (0)
; #define PG8_LDB(dst, b, h) do { _Pragma("unroll") for (int n = 0; n < 2; ++n) _Pragma("unroll") for (int k = 0; k < 2; ++k) dst[n][k] = *(const PG8_LAS bf16x8*)(lds + PG8_SB(b, h) + boff + n * 2048 + k * 1024); } while (0)
; #define PG8_MMA(ai, bj, At, Bt) do { __builtin_amdgcn_s_setprio(1); _Pragma("unroll") for (int m = 0; m < 4; ++m) _Pragma("unroll") for (int n = 0; n < 2; ++n) _Pragma("unroll") for (int k = 0; k < 2; ++k) \
;         acc[ai][bj][m][n] = __builtin_amdgcn_mfma_f32_16x16x32_bf16(Bt[n][k], At[m][k], acc[ai][bj][m][n], 0, 0, 0); __builtin_amdgcn_s_setprio(0); } while (0)
; #define PG8_WAIT_V(n) asm volatile("s_waitcnt vmcnt(" #n ")" ::: "memory")
; #define PG8_WAIT_L(n) asm volatile("s_waitcnt lgkmcnt(" #n ")" ::: "memory")
; #define PG8_BAR __builtin_amdgcn_s_barrier()
; #define PG8_SCHED __builtin_amdgcn_sched_barrier(0)
; template <class Epi, class Sched, bool ALIGN_EPI = false, bool SP2 = false>
; __device__ __forceinline__ void gemm_phase(PG8_LAS unsigned char* lds, const Gemm g, const Sched& S, const Epi& E) {
;     ...
;             PG8_WAIT_V(8); PG8_WAIT_L(0); PG8_BAR; PG8_MMA(1, 0, At, B0); PG8_MMA(1, 1, At, B1); PG8_BAR; PG8_SCHED;
;             PG8_LDB(B0, 1, 0); PG8_LDB(B1, 1, 1); PG8_SCHED; PG8_LDA(At, 1, 0); PG8_STAGE(PG8_SA(0, 1), a2 + hstep, voffA);
;             PG8_WAIT_V(8); PG8_WAIT_L(0); PG8_BAR; PG8_MMA(0, 0, At, B0); PG8_MMA(0, 1, At, B1); PG8_BAR; PG8_SCHED;
	v_mfma_f32_16x16x32_bf16 v[60:63], v[140:143], v[200:203], v[60:63]
	v_mfma_f32_16x16x32_bf16 v[56:59], v[160:163], v[200:203], v[56:59]
	v_mfma_f32_16x16x32_bf16 v[44:47], v[140:143], v[208:211], v[44:47]
	v_mfma_f32_16x16x32_bf16 v[40:43], v[160:163], v[208:211], v[40:43]
	v_mfma_f32_16x16x32_bf16 v[28:31], v[140:143], v[216:219], v[28:31]
	v_mfma_f32_16x16x32_bf16 v[24:27], v[160:163], v[216:219], v[24:27]
	v_mfma_f32_16x16x32_bf16 v[12:15], v[140:143], v[224:227], v[12:15]
	v_mfma_f32_16x16x32_bf16 v[8:11], v[160:163], v[224:227], v[8:11]
	v_mfma_f32_16x16x32_bf16 v[60:63], v[156:159], v[204:207], v[60:63]
	v_mfma_f32_16x16x32_bf16 v[56:59], v[164:167], v[204:207], v[56:59]
	v_mfma_f32_16x16x32_bf16 v[44:47], v[156:159], v[212:215], v[44:47]
	v_mfma_f32_16x16x32_bf16 v[40:43], v[164:167], v[212:215], v[40:43]
	v_mfma_f32_16x16x32_bf16 v[28:31], v[156:159], v[220:223], v[28:31]
	v_mfma_f32_16x16x32_bf16 v[24:27], v[164:167], v[220:223], v[24:27]
	v_mfma_f32_16x16x32_bf16 v[12:15], v[156:159], v[228:231], v[12:15]
	v_mfma_f32_16x16x32_bf16 v[8:11], v[164:167], v[228:231], v[8:11]
	v_mfma_f32_16x16x32_bf16 v[52:55], v[168:171], v[200:203], v[52:55]
	v_mfma_f32_16x16x32_bf16 v[48:51], v[192:195], v[200:203], v[48:51]
	v_mfma_f32_16x16x32_bf16 v[36:39], v[168:171], v[208:211], v[36:39]
	v_mfma_f32_16x16x32_bf16 v[32:35], v[192:195], v[208:211], v[32:35]
	v_mfma_f32_16x16x32_bf16 v[20:23], v[168:171], v[216:219], v[20:23]
	v_mfma_f32_16x16x32_bf16 v[16:19], v[192:195], v[216:219], v[16:19]
	v_mfma_f32_16x16x32_bf16 v[4:7], v[168:171], v[224:227], v[4:7]
	v_mfma_f32_16x16x32_bf16 v[0:3], v[192:195], v[224:227], v[0:3]
	v_mfma_f32_16x16x32_bf16 v[52:55], v[172:175], v[204:207], v[52:55]
	v_mfma_f32_16x16x32_bf16 v[48:51], v[196:199], v[204:207], v[48:51]
	v_mfma_f32_16x16x32_bf16 v[36:39], v[172:175], v[212:215], v[36:39]
	v_mfma_f32_16x16x32_bf16 v[32:35], v[196:199], v[212:215], v[32:35]
	v_mfma_f32_16x16x32_bf16 v[20:23], v[172:175], v[220:223], v[20:23]
	v_mfma_f32_16x16x32_bf16 v[16:19], v[196:199], v[220:223], v[16:19]
	v_mfma_f32_16x16x32_bf16 v[4:7], v[172:175], v[228:231], v[4:7]
	v_mfma_f32_16x16x32_bf16 v[0:3], v[196:199], v[228:231], v[0:3]
	s_barrier
	s_setprio 0
	v_add_u32_e32 v144, s93, v147
	s_add_i32 s82, 0, 0x1c000
	ds_read_b128 v[140:143], v144
	ds_read_b128 v[156:159], v144 offset:1024
	ds_read_b128 v[160:163], v144 offset:2048
	ds_read_b128 v[164:167], v144 offset:3072
	v_add_u32_e32 v144, s82, v147
	ds_read_b128 v[168:171], v144
	ds_read_b128 v[172:175], v144 offset:1024
	ds_read_b128 v[192:195], v144 offset:2048
	ds_read_b128 v[196:199], v144 offset:3072
	s_add_u32 s68, s80, 0x80000
	s_addc_u32 s69, s81, 0
	s_mov_b32 m0, s16
	v_lshl_add_u64 v[190:191], s[68:69], 0, v[132:133]
	ds_read_b128 v[200:203], v149 offset:32768
	ds_read_b128 v[204:207], v149 offset:33792
	ds_read_b128 v[208:211], v149 offset:34816
	ds_read_b128 v[212:215], v149 offset:35840
	ds_read_b128 v[216:219], v149 offset:36864
	ds_read_b128 v[220:223], v149 offset:37888
	ds_read_b128 v[224:227], v149 offset:38912
	ds_read_b128 v[228:231], v149 offset:39936
	global_load_lds_dwordx4 v[190:191], off
	v_lshl_add_u64 v[190:191], s[68:69], 0, v[130:131]
	s_mov_b32 m0, s17
	s_nop 0
	global_load_lds_dwordx4 v[190:191], off
	s_waitcnt vmcnt(8)
	s_waitcnt lgkmcnt(0)
	s_setprio 1
	s_barrier
	v_mfma_f32_16x16x32_bf16 v[124:127], v[140:143], v[200:203], v[124:127]
	v_mfma_f32_16x16x32_bf16 v[120:123], v[160:163], v[200:203], v[120:123]
	v_mfma_f32_16x16x32_bf16 v[108:111], v[140:143], v[208:211], v[108:111]
	v_mfma_f32_16x16x32_bf16 v[104:107], v[160:163], v[208:211], v[104:107]
	v_mfma_f32_16x16x32_bf16 v[92:95], v[140:143], v[216:219], v[92:95]
	v_mfma_f32_16x16x32_bf16 v[88:91], v[160:163], v[216:219], v[88:91]
	v_mfma_f32_16x16x32_bf16 v[76:79], v[140:143], v[224:227], v[76:79]
	v_mfma_f32_16x16x32_bf16 v[72:75], v[160:163], v[224:227], v[72:75]
	v_mfma_f32_16x16x32_bf16 v[124:127], v[156:159], v[204:207], v[124:127]
	v_mfma_f32_16x16x32_bf16 v[120:123], v[164:167], v[204:207], v[120:123]
	v_mfma_f32_16x16x32_bf16 v[108:111], v[156:159], v[212:215], v[108:111]
	v_mfma_f32_16x16x32_bf16 v[104:107], v[164:167], v[212:215], v[104:107]
	v_mfma_f32_16x16x32_bf16 v[92:95], v[156:159], v[220:223], v[92:95]
	v_mfma_f32_16x16x32_bf16 v[88:91], v[164:167], v[220:223], v[88:91]
	v_mfma_f32_16x16x32_bf16 v[76:79], v[156:159], v[228:231], v[76:79]
	v_mfma_f32_16x16x32_bf16 v[72:75], v[164:167], v[228:231], v[72:75]
	v_mfma_f32_16x16x32_bf16 v[116:119], v[168:171], v[200:203], v[116:119]
	v_mfma_f32_16x16x32_bf16 v[112:115], v[192:195], v[200:203], v[112:115]
	v_mfma_f32_16x16x32_bf16 v[100:103], v[168:171], v[208:211], v[100:103]
	v_mfma_f32_16x16x32_bf16 v[96:99], v[192:195], v[208:211], v[96:99]
	v_mfma_f32_16x16x32_bf16 v[84:87], v[168:171], v[216:219], v[84:87]
	v_mfma_f32_16x16x32_bf16 v[80:83], v[192:195], v[216:219], v[80:83]
	v_mfma_f32_16x16x32_bf16 v[68:71], v[168:171], v[224:227], v[68:71]
	v_mfma_f32_16x16x32_bf16 v[64:67], v[192:195], v[224:227], v[64:67]
	v_mfma_f32_16x16x32_bf16 v[116:119], v[172:175], v[204:207], v[116:119]
	v_mfma_f32_16x16x32_bf16 v[112:115], v[196:199], v[204:207], v[112:115]
	v_mfma_f32_16x16x32_bf16 v[100:103], v[172:175], v[212:215], v[100:103]
	v_mfma_f32_16x16x32_bf16 v[96:99], v[196:199], v[212:215], v[96:99]
	v_mfma_f32_16x16x32_bf16 v[84:87], v[172:175], v[220:223], v[84:87]
	v_mfma_f32_16x16x32_bf16 v[80:83], v[196:199], v[220:223], v[80:83]
	v_mfma_f32_16x16x32_bf16 v[68:71], v[172:175], v[228:231], v[68:71]
	v_mfma_f32_16x16x32_bf16 v[64:67], v[196:199], v[228:231], v[64:67]
	s_barrier
; #define PG8_STAGE(bufoff, gbase, voff) do { _Pragma("unroll") for (int _i = 0; _i < 2; ++_i) \
;         __builtin_amdgcn_global_load_lds((const unsigned*)((const char*)(gbase) + (voff)[_i]), (PG8_LAS unsigned*)(lds + (bufoff) + ldsw + _i * 8192), 16, 0, 0); } while (0)
; #define PG8_LDA(dst, b, h) do { _Pragma("unroll") for (int m = 0; m < 4; ++m) _Pragma("unroll") for (int k = 0; k < 2; ++k) dst[m][k] = *(const PG8_LAS bf16x8*)(lds + PG8_SA(b, h) + aoff + m * 2048 + k * 1024); } while (0)
; #define PG8_MMA(ai, bj, At, Bt) do { __builtin_amdgcn_s_setprio(1); _Pragma("unroll") for (int m = 0; m < 4; ++m) _Pragma("unroll") for (int n = 0; n < 2; ++n) _Pragma("unroll") for (int k = 0; k < 2; ++k) \
;         acc[ai][bj][m][n] = __builtin_amdgcn_mfma_f32_16x16x32_bf16(Bt[n][k], At[m][k], acc[ai][bj][m][n], 0, 0, 0); __builtin_amdgcn_s_setprio(0); } while (0)
; #define PG8_WAIT_V(n) asm volatile("s_waitcnt vmcnt(" #n ")" ::: "memory")
; #define PG8_WAIT_L(n) asm volatile("s_waitcnt lgkmcnt(" #n ")" ::: "memory")
; #define PG8_BAR __builtin_amdgcn_s_barrier()
; #define PG8_SCHED __builtin_amdgcn_sched_barrier(0)
; template <class Epi, class Sched, bool ALIGN_EPI = false, bool SP2 = false>
; __device__ __forceinline__ void gemm_phase(PG8_LAS unsigned char* lds, const Gemm g, const Sched& S, const Epi& E) {
;     ...
;         for (int t = 0; t < nt; t += 2) {
;             const bool last = (t == nt - 2);
;             const char* a1 = cA + (size_t)(t + 1) * kstep;
;             const char* a2 = last ? nA : cA + (size_t)(t + 2) * kstep; const char* b2 = last ? nB : cB + (size_t)(t + 2) * kstep;
;             const char* a3 = a2 + kstep; const char* b3 = b2 + kstep;
;     ...
;             PG8_WAIT_V(8); PG8_WAIT_L(0); PG8_BAR; PG8_MMA(0, 0, At, B0); PG8_MMA(0, 1, At, B1); PG8_BAR; PG8_SCHED;
;             PG8_LDA(At, 1, 1); PG8_STAGE(PG8_SB(1, 0), b3, voffB); PG8_STAGE(PG8_SB(1, 1), b3 + hstep, voffB); PG8_STAGE(PG8_SA(1, 0), a3, voffA);
;             PG8_WAIT_V(8); PG8_WAIT_L(0); PG8_BAR; PG8_MMA(1, 0, At, B0); PG8_MMA(1, 1, At, B1); PG8_BAR; PG8_SCHED;
	s_setprio 0
	s_add_i32 s68, s93, s0
	v_lshl_add_u64 v[150:151], v[150:151], 0, s[18:19]
	s_mov_b32 m0, s68
	ds_read_b128 v[200:203], v149 offset:49152
	ds_read_b128 v[204:207], v149 offset:50176
	ds_read_b128 v[208:211], v149 offset:51200
	ds_read_b128 v[212:215], v149 offset:52224
	ds_read_b128 v[216:219], v149 offset:53248
	ds_read_b128 v[220:223], v149 offset:54272
	ds_read_b128 v[224:227], v149 offset:55296
	ds_read_b128 v[228:231], v149 offset:56320
	global_load_lds_dwordx4 v[150:151], off
	s_add_i32 m0, s68, 0x2000
	s_add_u32 s68, s78, 0x80080
	v_lshl_add_u64 v[150:151], v[182:183], 0, s[18:19]
	s_addc_u32 s69, s79, 0
	s_add_i32 s78, s82, s0
	global_load_lds_dwordx4 v[150:151], off
	v_lshl_add_u64 v[150:151], s[68:69], 0, v[152:153]
	s_mov_b32 m0, s78
	s_nop 0
	global_load_lds_dwordx4 v[150:151], off
	v_lshl_add_u64 v[150:151], s[68:69], 0, v[128:129]
	s_add_i32 m0, s78, 0x2000
	s_nop 0
	global_load_lds_dwordx4 v[150:151], off
	v_lshl_add_u64 v[150:151], v[184:185], 0, s[18:19]
	s_mov_b32 m0, s22
	s_nop 0
	global_load_lds_dwordx4 v[150:151], off
	v_lshl_add_u64 v[150:151], v[188:189], 0, s[18:19]
	s_mov_b32 m0, s23
	s_nop 0
	global_load_lds_dwordx4 v[150:151], off
	s_waitcnt vmcnt(8)
	s_waitcnt lgkmcnt(0)
	s_setprio 1
	s_barrier
	v_mfma_f32_16x16x32_bf16 v[60:63], v[140:143], v[200:203], v[60:63]
	v_mfma_f32_16x16x32_bf16 v[56:59], v[160:163], v[200:203], v[56:59]
	v_mfma_f32_16x16x32_bf16 v[44:47], v[140:143], v[208:211], v[44:47]
	v_mfma_f32_16x16x32_bf16 v[40:43], v[160:163], v[208:211], v[40:43]
	v_mfma_f32_16x16x32_bf16 v[28:31], v[140:143], v[216:219], v[28:31]
	v_mfma_f32_16x16x32_bf16 v[24:27], v[160:163], v[216:219], v[24:27]
	v_mfma_f32_16x16x32_bf16 v[12:15], v[140:143], v[224:227], v[12:15]
	v_mfma_f32_16x16x32_bf16 v[8:11], v[160:163], v[224:227], v[8:11]
	v_mfma_f32_16x16x32_bf16 v[60:63], v[156:159], v[204:207], v[60:63]
	v_mfma_f32_16x16x32_bf16 v[56:59], v[164:167], v[204:207], v[56:59]
	v_mfma_f32_16x16x32_bf16 v[44:47], v[156:159], v[212:215], v[44:47]
	v_mfma_f32_16x16x32_bf16 v[40:43], v[164:167], v[212:215], v[40:43]
	v_mfma_f32_16x16x32_bf16 v[28:31], v[156:159], v[220:223], v[28:31]
	v_mfma_f32_16x16x32_bf16 v[24:27], v[164:167], v[220:223], v[24:27]
	v_mfma_f32_16x16x32_bf16 v[12:15], v[156:159], v[228:231], v[12:15]
	v_mfma_f32_16x16x32_bf16 v[8:11], v[164:167], v[228:231], v[8:11]
	v_mfma_f32_16x16x32_bf16 v[52:55], v[168:171], v[200:203], v[52:55]
	v_mfma_f32_16x16x32_bf16 v[48:51], v[192:195], v[200:203], v[48:51]
	v_mfma_f32_16x16x32_bf16 v[36:39], v[168:171], v[208:211], v[36:39]
	v_mfma_f32_16x16x32_bf16 v[32:35], v[192:195], v[208:211], v[32:35]
	v_mfma_f32_16x16x32_bf16 v[20:23], v[168:171], v[216:219], v[20:23]
	v_mfma_f32_16x16x32_bf16 v[16:19], v[192:195], v[216:219], v[16:19]
	v_mfma_f32_16x16x32_bf16 v[4:7], v[168:171], v[224:227], v[4:7]
	v_mfma_f32_16x16x32_bf16 v[0:3], v[192:195], v[224:227], v[0:3]
	v_mfma_f32_16x16x32_bf16 v[52:55], v[172:175], v[204:207], v[52:55]
	v_mfma_f32_16x16x32_bf16 v[48:51], v[196:199], v[204:207], v[48:51]
	v_mfma_f32_16x16x32_bf16 v[36:39], v[172:175], v[212:215], v[36:39]
	v_mfma_f32_16x16x32_bf16 v[32:35], v[196:199], v[212:215], v[32:35]
	v_mfma_f32_16x16x32_bf16 v[20:23], v[172:175], v[220:223], v[20:23]
	v_mfma_f32_16x16x32_bf16 v[16:19], v[196:199], v[220:223], v[16:19]
	v_mfma_f32_16x16x32_bf16 v[4:7], v[172:175], v[228:231], v[4:7]
	v_mfma_f32_16x16x32_bf16 v[0:3], v[196:199], v[228:231], v[0:3]
	s_barrier
	s_setprio 0
	s_add_i32 s71, s71, 2
	s_add_u32 s42, s42, 0x100
	s_addc_u32 s43, s43, 0
	s_add_u32 s59, s59, 0x100
	s_addc_u32 s63, s63, 0
	s_cmp_gt_u32 s71, 29
	s_cbranch_scc0 .LBB0_165
	s_and_b64 vcc, exec, s[24:25]
	s_cbranch_vccz .LBB0_168
	s_barrier

; #define PG8_STAGE(bufoff, gbase, voff) do { _Pragma("unroll") for (int _i = 0; _i < 2; ++_i) \
;         __builtin_amdgcn_global_load_lds((const unsigned*)((const char*)(gbase) + (voff)[_i]), (PG8_LAS unsigned*)(lds + (bufoff) + ldsw + _i * 8192), 16, 0, 0); } while (0)
; #define PG8_LDA(dst, b, h) do { _Pragma("unroll") for (int m = 0; m < 4; ++m) _Pragma("unroll") for (int k = 0; k < 2; ++k) dst[m][k] = *(const PG8_LAS bf16x8*)(lds + PG8_SA(b, h) + aoff + m * 2048 + k * 1024); } while (0)
; #define PG8_LDB(dst, b, h) do { _Pragma("unroll") for (int n = 0; n < 2; ++n) _Pragma("unroll") for (int k = 0; k < 2; ++k) dst[n][k] = *(const PG8_LAS bf16x8*)(lds + PG8_SB(b, h) + boff + n * 2048 + k * 1024); } while (0)
; #define PG8_MMA(ai, bj, At, Bt) do { __builtin_amdgcn_s_setprio(1); _Pragma("unroll") for (int m = 0; m < 4; ++m) _Pragma("unroll") for (int n = 0; n < 2; ++n) _Pragma("unroll") for (int k = 0; k < 2; ++k) \
;         acc[ai][bj][m][n] = __builtin_amdgcn_mfma_f32_16x16x32_bf16(Bt[n][k], At[m][k], acc[ai][bj][m][n], 0, 0, 0); __builtin_amdgcn_s_setprio(0); } while (0)
; #define PG8_WAIT_V(n) asm volatile("s_waitcnt vmcnt(" #n ")" ::: "memory")
; #define PG8_WAIT_L(n) asm volatile("s_waitcnt lgkmcnt(" #n ")" ::: "memory")
; #define PG8_BAR __builtin_amdgcn_s_barrier()
; #define PG8_SCHED __builtin_amdgcn_sched_barrier(0)
; template <class Epi, class Sched, bool ALIGN_EPI = false, bool SP2 = false>
; __device__ __forceinline__ void gemm_phase(PG8_LAS unsigned char* lds, const Gemm g, const Sched& S, const Epi& E) {
;     ...
;             const bool last = (t == nt - 2);
;             const char* a1 = cA + (size_t)(t + 1) * kstep;
;             const char* a2 = last ? nA : cA + (size_t)(t + 2) * kstep; const char* b2 = last ? nB : cB + (size_t)(t + 2) * kstep;
;             const char* a3 = a2 + kstep; const char* b3 = b2 + kstep;
;             if (last && has_next) S.a_ready(nxt);
;             if constexpr (SP2) {
;             PG8_LDB(B0, 0, 0); PG8_LDB(B1, 0, 1); PG8_SCHED; PG8_LDA(At, 0, 0); PG8_STAGE(PG8_SA(1, 1), a1 + hstep, voffA);
;             PG8_WAIT_V(8); PG8_WAIT_L(0); PG8_BAR; PG8_MMA(0, 0, At, B0); PG8_MMA(0, 1, At, B1); PG8_BAR; PG8_SCHED;
;             PG8_LDA(At, 0, 1); PG8_STAGE(PG8_SB(0, 0), b2, voffB); PG8_STAGE(PG8_SB(0, 1), b2 + hstep, voffB); PG8_STAGE(PG8_SA(0, 0), a2, voffA);
.LBB0_218:
	s_add_i32 vcc_lo, s46, 2
	s_add_u32 s68, s44, 0x80
	s_addc_u32 s47, s45, 0
	s_add_i32 vcc_hi, 0, 0x10000
	s_cmp_eq_u32 s15, s46
	s_cselect_b32 s47, s83, s47
	s_cselect_b32 s46, s82, s68
	v_add_u32_e32 v146, vcc_hi, v149
	s_cselect_b32 s69, s85, s87
	s_cselect_b32 s68, s84, s86
	s_add_i32 s96, 0, 0x14000
	ds_read_b128 v[138:141], v146
	ds_read_b128 v[142:145], v146 offset:1024
	ds_read_b128 v[156:159], v146 offset:2048
	ds_read_b128 v[160:163], v146 offset:3072
	v_add_u32_e32 v146, s96, v149
	ds_read_b128 v[164:167], v146
	ds_read_b128 v[168:171], v146 offset:1024
	ds_read_b128 v[172:175], v146 offset:2048
	ds_read_b128 v[192:195], v146 offset:3072
	v_lshl_add_u64 v[146:147], s[44:45], 0, v[134:135]
	s_add_i32 m0, s54, 0xc000
	ds_read_b128 v[196:199], v151
	ds_read_b128 v[200:203], v151 offset:1024
	ds_read_b128 v[204:207], v151 offset:2048
	ds_read_b128 v[208:211], v151 offset:3072
	ds_read_b128 v[212:215], v151 offset:4096
	ds_read_b128 v[216:219], v151 offset:5120
	ds_read_b128 v[220:223], v151 offset:6144
	ds_read_b128 v[224:227], v151 offset:7168
	global_load_lds_dwordx4 v[146:147], off
	v_lshl_add_u64 v[146:147], s[44:45], 0, v[136:137]
	s_add_i32 m0, s54, 0xe000
	s_nop 0
	global_load_lds_dwordx4 v[146:147], off
	s_waitcnt vmcnt(8)
	s_waitcnt lgkmcnt(0)
	s_setprio 1
	s_barrier
	v_mfma_f32_16x16x32_bf16 v[124:127], v[138:141], v[196:199], v[124:127]
	v_mfma_f32_16x16x32_bf16 v[120:123], v[156:159], v[196:199], v[120:123]
	v_mfma_f32_16x16x32_bf16 v[108:111], v[138:141], v[204:207], v[108:111]
	v_mfma_f32_16x16x32_bf16 v[104:107], v[156:159], v[204:207], v[104:107]
	v_mfma_f32_16x16x32_bf16 v[92:95], v[138:141], v[212:215], v[92:95]
	v_mfma_f32_16x16x32_bf16 v[88:91], v[156:159], v[212:215], v[88:91]
	v_mfma_f32_16x16x32_bf16 v[76:79], v[138:141], v[220:223], v[76:79]
	v_mfma_f32_16x16x32_bf16 v[72:75], v[156:159], v[220:223], v[72:75]
	v_mfma_f32_16x16x32_bf16 v[124:127], v[142:145], v[200:203], v[124:127]
	v_mfma_f32_16x16x32_bf16 v[120:123], v[160:163], v[200:203], v[120:123]
	v_mfma_f32_16x16x32_bf16 v[108:111], v[142:145], v[208:211], v[108:111]
	v_mfma_f32_16x16x32_bf16 v[104:107], v[160:163], v[208:211], v[104:107]
	v_mfma_f32_16x16x32_bf16 v[92:95], v[142:145], v[216:219], v[92:95]
	v_mfma_f32_16x16x32_bf16 v[88:91], v[160:163], v[216:219], v[88:91]
	v_mfma_f32_16x16x32_bf16 v[76:79], v[142:145], v[224:227], v[76:79]
	v_mfma_f32_16x16x32_bf16 v[72:75], v[160:163], v[224:227], v[72:75]
	v_mfma_f32_16x16x32_bf16 v[116:119], v[164:167], v[196:199], v[116:119]
	v_mfma_f32_16x16x32_bf16 v[112:115], v[172:175], v[196:199], v[112:115]
	v_mfma_f32_16x16x32_bf16 v[100:103], v[164:167], v[204:207], v[100:103]
	v_mfma_f32_16x16x32_bf16 v[96:99], v[172:175], v[204:207], v[96:99]
	v_mfma_f32_16x16x32_bf16 v[84:87], v[164:167], v[212:215], v[84:87]
	v_mfma_f32_16x16x32_bf16 v[80:83], v[172:175], v[212:215], v[80:83]
	v_mfma_f32_16x16x32_bf16 v[68:71], v[164:167], v[220:223], v[68:71]
	v_mfma_f32_16x16x32_bf16 v[64:67], v[172:175], v[220:223], v[64:67]
	v_mfma_f32_16x16x32_bf16 v[116:119], v[168:171], v[200:203], v[116:119]
	v_mfma_f32_16x16x32_bf16 v[112:115], v[192:195], v[200:203], v[112:115]
	v_mfma_f32_16x16x32_bf16 v[100:103], v[168:171], v[208:211], v[100:103]
	v_mfma_f32_16x16x32_bf16 v[96:99], v[192:195], v[208:211], v[96:99]
	v_mfma_f32_16x16x32_bf16 v[84:87], v[168:171], v[216:219], v[84:87]
	v_mfma_f32_16x16x32_bf16 v[80:83], v[192:195], v[216:219], v[80:83]
	v_mfma_f32_16x16x32_bf16 v[68:71], v[168:171], v[224:227], v[68:71]
	v_mfma_f32_16x16x32_bf16 v[64:67], v[192:195], v[224:227], v[64:67]
	s_barrier
	s_setprio 0
	s_add_i32 vcc_hi, vcc_hi, s63
	v_lshl_add_u64 v[146:147], s[68:69], 0, v[152:153]
	s_mov_b32 m0, vcc_hi
	ds_read_b128 v[196:199], v151 offset:16384
	ds_read_b128 v[200:203], v151 offset:17408
	ds_read_b128 v[204:207], v151 offset:18432
	ds_read_b128 v[208:211], v151 offset:19456
	ds_read_b128 v[212:215], v151 offset:20480
	ds_read_b128 v[216:219], v151 offset:21504
	ds_read_b128 v[220:223], v151 offset:22528
	ds_read_b128 v[224:227], v151 offset:23552
	global_load_lds_dwordx4 v[146:147], off
	s_add_i32 m0, vcc_hi, 0x2000
	v_lshl_add_u64 v[182:183], s[68:69], 0, v[128:129]
	s_add_u32 s68, s68, s48
	s_addc_u32 s69, s69, 0
	s_add_i32 s96, s96, s63
	global_load_lds_dwordx4 v[182:183], off
	v_lshl_add_u64 v[184:185], s[68:69], 0, v[152:153]
	s_mov_b32 m0, s96
	v_lshl_add_u64 v[188:189], s[68:69], 0, v[128:129]
	global_load_lds_dwordx4 v[184:185], off
	s_add_i32 m0, s96, 0x2000
	v_lshl_add_u64 v[190:191], s[46:47], 0, v[132:133]
	global_load_lds_dwordx4 v[188:189], off
	s_mov_b32 m0, s54
	v_lshl_add_u64 v[228:229], s[46:47], 0, v[130:131]
	global_load_lds_dwordx4 v[190:191], off
	s_mov_b32 m0, s55
	s_nop 0
	global_load_lds_dwordx4 v[228:229], off
	s_waitcnt vmcnt(8)
	s_waitcnt lgkmcnt(0)
	s_setprio 1
	s_barrier
; #define PG8_STAGE(bufoff, gbase, voff) do { _Pragma("unroll") for (int _i = 0; _i < 2; ++_i) \
;         __builtin_amdgcn_global_load_lds((const unsigned*)((const char*)(gbase) + (voff)[_i]), (PG8_LAS unsigned*)(lds + (bufoff) + ldsw + _i * 8192), 16, 0, 0); } while (0)
; #define PG8_LDA(dst, b, h) do { _Pragma("unroll") for (int m = 0; m < 4; ++m) _Pragma("unroll") for (int k = 0; k < 2; ++k) dst[m][k] = *(const PG8_LAS bf16x8*)(lds + PG8_SA(b, h) + aoff + m * 2048 + k * 1024); } while (0)
; #define PG8_LDB(dst, b, h) do { _Pragma("unroll") for (int n = 0; n < 2; ++n) _Pragma("unroll") for (int k = 0; k < 2; ++k) dst[n][k] = *(const PG8_LAS bf16x8*)(lds + PG8_SB(b, h) + boff + n * 2048 + k * 1024); } while (0)
; #define PG8_MMA(ai, bj, At, Bt) do { __builtin_amdgcn_s_setprio(1); _Pragma("unroll") for (int m = 0; m < 4; ++m) _Pragma("unroll") for (int n = 0; n < 2; ++n) _Pragma("unroll") for (int k = 0; k < 2; ++k) \
;         acc[ai][bj][m][n] = __builtin_amdgcn_mfma_f32_16x16x32_bf16(Bt[n][k], At[m][k], acc[ai][bj][m][n], 0, 0, 0); __builtin_amdgcn_s_setprio(0); } while (0)
; #define PG8_WAIT_V(n) asm volatile("s_waitcnt vmcnt(" #n ")" ::: "memory")
; #define PG8_WAIT_L(n) asm volatile("s_waitcnt lgkmcnt(" #n ")" ::: "memory")
; #define PG8_BAR __builtin_amdgcn_s_barrier()
; #define PG8_SCHED __builtin_amdgcn_sched_barrier(0)
; template <class Epi, class Sched, bool ALIGN_EPI = false, bool SP2 = false>
; __device__ __forceinline__ void gemm_phase(PG8_LAS unsigned char* lds, const Gemm g, const Sched& S, const Epi& E) {
;     ...
;             PG8_WAIT_V(8); PG8_WAIT_L(0); PG8_BAR; PG8_MMA(1, 0, At, B0); PG8_MMA(1, 1, At, B1); PG8_BAR; PG8_SCHED;
;             PG8_LDB(B0, 1, 0); PG8_LDB(B1, 1, 1); PG8_SCHED; PG8_LDA(At, 1, 0); PG8_STAGE(PG8_SA(0, 1), a2 + hstep, voffA);
;             PG8_WAIT_V(8); PG8_WAIT_L(0); PG8_BAR; PG8_MMA(0, 0, At, B0); PG8_MMA(0, 1, At, B1); PG8_BAR; PG8_SCHED;
	v_mfma_f32_16x16x32_bf16 v[60:63], v[138:141], v[196:199], v[60:63]
	v_mfma_f32_16x16x32_bf16 v[56:59], v[156:159], v[196:199], v[56:59]
	v_mfma_f32_16x16x32_bf16 v[44:47], v[138:141], v[204:207], v[44:47]
	v_mfma_f32_16x16x32_bf16 v[40:43], v[156:159], v[204:207], v[40:43]
	v_mfma_f32_16x16x32_bf16 v[28:31], v[138:141], v[212:215], v[28:31]
	v_mfma_f32_16x16x32_bf16 v[24:27], v[156:159], v[212:215], v[24:27]
	v_mfma_f32_16x16x32_bf16 v[12:15], v[138:141], v[220:223], v[12:15]
	v_mfma_f32_16x16x32_bf16 v[8:11], v[156:159], v[220:223], v[8:11]
	v_mfma_f32_16x16x32_bf16 v[60:63], v[142:145], v[200:203], v[60:63]
	v_mfma_f32_16x16x32_bf16 v[56:59], v[160:163], v[200:203], v[56:59]
	v_mfma_f32_16x16x32_bf16 v[44:47], v[142:145], v[208:211], v[44:47]
	v_mfma_f32_16x16x32_bf16 v[40:43], v[160:163], v[208:211], v[40:43]
	v_mfma_f32_16x16x32_bf16 v[28:31], v[142:145], v[216:219], v[28:31]
	v_mfma_f32_16x16x32_bf16 v[24:27], v[160:163], v[216:219], v[24:27]
	v_mfma_f32_16x16x32_bf16 v[12:15], v[142:145], v[224:227], v[12:15]
	v_mfma_f32_16x16x32_bf16 v[8:11], v[160:163], v[224:227], v[8:11]
	v_mfma_f32_16x16x32_bf16 v[52:55], v[164:167], v[196:199], v[52:55]
	v_mfma_f32_16x16x32_bf16 v[48:51], v[172:175], v[196:199], v[48:51]
	v_mfma_f32_16x16x32_bf16 v[36:39], v[164:167], v[204:207], v[36:39]
	v_mfma_f32_16x16x32_bf16 v[32:35], v[172:175], v[204:207], v[32:35]
	v_mfma_f32_16x16x32_bf16 v[20:23], v[164:167], v[212:215], v[20:23]
	v_mfma_f32_16x16x32_bf16 v[16:19], v[172:175], v[212:215], v[16:19]
	v_mfma_f32_16x16x32_bf16 v[4:7], v[164:167], v[220:223], v[4:7]
	v_mfma_f32_16x16x32_bf16 v[0:3], v[172:175], v[220:223], v[0:3]
	v_mfma_f32_16x16x32_bf16 v[52:55], v[168:171], v[200:203], v[52:55]
	v_mfma_f32_16x16x32_bf16 v[48:51], v[192:195], v[200:203], v[48:51]
	v_mfma_f32_16x16x32_bf16 v[36:39], v[168:171], v[208:211], v[36:39]
	v_mfma_f32_16x16x32_bf16 v[32:35], v[192:195], v[208:211], v[32:35]
	v_mfma_f32_16x16x32_bf16 v[20:23], v[168:171], v[216:219], v[20:23]
	v_mfma_f32_16x16x32_bf16 v[16:19], v[192:195], v[216:219], v[16:19]
	v_mfma_f32_16x16x32_bf16 v[4:7], v[168:171], v[224:227], v[4:7]
	v_mfma_f32_16x16x32_bf16 v[0:3], v[192:195], v[224:227], v[0:3]
	s_barrier
	s_setprio 0
	v_add_u32_e32 v155, s93, v149
	s_add_i32 s68, 0, 0x1c000
	ds_read_b128 v[138:141], v155
	ds_read_b128 v[142:145], v155 offset:1024
	ds_read_b128 v[156:159], v155 offset:2048
	ds_read_b128 v[160:163], v155 offset:3072
	v_add_u32_e32 v155, s68, v149
	ds_read_b128 v[164:167], v155
	ds_read_b128 v[168:171], v155 offset:1024
	ds_read_b128 v[172:175], v155 offset:2048
	ds_read_b128 v[192:195], v155 offset:3072
	s_add_u32 s46, s46, s48
	s_addc_u32 s47, s47, 0
	s_mov_b32 m0, s34
	v_lshl_add_u64 v[230:231], s[46:47], 0, v[132:133]
	ds_read_b128 v[196:199], v151 offset:32768
	ds_read_b128 v[200:203], v151 offset:33792
	ds_read_b128 v[204:207], v151 offset:34816
	ds_read_b128 v[208:211], v151 offset:35840
	ds_read_b128 v[212:215], v151 offset:36864
	ds_read_b128 v[216:219], v151 offset:37888
	ds_read_b128 v[220:223], v151 offset:38912
	ds_read_b128 v[224:227], v151 offset:39936
	global_load_lds_dwordx4 v[230:231], off
	v_lshl_add_u64 v[230:231], s[46:47], 0, v[130:131]
	s_mov_b32 m0, s95
	s_nop 0
	global_load_lds_dwordx4 v[230:231], off
	s_waitcnt vmcnt(8)
	s_waitcnt lgkmcnt(0)
	s_setprio 1
	s_barrier
	v_mfma_f32_16x16x32_bf16 v[124:127], v[138:141], v[196:199], v[124:127]
	v_mfma_f32_16x16x32_bf16 v[120:123], v[156:159], v[196:199], v[120:123]
	v_mfma_f32_16x16x32_bf16 v[108:111], v[138:141], v[204:207], v[108:111]
	v_mfma_f32_16x16x32_bf16 v[104:107], v[156:159], v[204:207], v[104:107]
	v_mfma_f32_16x16x32_bf16 v[92:95], v[138:141], v[212:215], v[92:95]
	v_mfma_f32_16x16x32_bf16 v[88:91], v[156:159], v[212:215], v[88:91]
	v_mfma_f32_16x16x32_bf16 v[76:79], v[138:141], v[220:223], v[76:79]
	v_mfma_f32_16x16x32_bf16 v[72:75], v[156:159], v[220:223], v[72:75]
	v_mfma_f32_16x16x32_bf16 v[124:127], v[142:145], v[200:203], v[124:127]
	v_mfma_f32_16x16x32_bf16 v[120:123], v[160:163], v[200:203], v[120:123]
	v_mfma_f32_16x16x32_bf16 v[108:111], v[142:145], v[208:211], v[108:111]
	v_mfma_f32_16x16x32_bf16 v[104:107], v[160:163], v[208:211], v[104:107]
	v_mfma_f32_16x16x32_bf16 v[92:95], v[142:145], v[216:219], v[92:95]
	v_mfma_f32_16x16x32_bf16 v[88:91], v[160:163], v[216:219], v[88:91]
	v_mfma_f32_16x16x32_bf16 v[76:79], v[142:145], v[224:227], v[76:79]
	v_mfma_f32_16x16x32_bf16 v[72:75], v[160:163], v[224:227], v[72:75]
	v_mfma_f32_16x16x32_bf16 v[116:119], v[164:167], v[196:199], v[116:119]
	v_mfma_f32_16x16x32_bf16 v[112:115], v[172:175], v[196:199], v[112:115]
	v_mfma_f32_16x16x32_bf16 v[100:103], v[164:167], v[204:207], v[100:103]
	v_mfma_f32_16x16x32_bf16 v[96:99], v[172:175], v[204:207], v[96:99]
	v_mfma_f32_16x16x32_bf16 v[84:87], v[164:167], v[212:215], v[84:87]
	v_mfma_f32_16x16x32_bf16 v[80:83], v[172:175], v[212:215], v[80:83]
	v_mfma_f32_16x16x32_bf16 v[68:71], v[164:167], v[220:223], v[68:71]
	v_mfma_f32_16x16x32_bf16 v[64:67], v[172:175], v[220:223], v[64:67]
	v_mfma_f32_16x16x32_bf16 v[116:119], v[168:171], v[200:203], v[116:119]
	v_mfma_f32_16x16x32_bf16 v[112:115], v[192:195], v[200:203], v[112:115]
	v_mfma_f32_16x16x32_bf16 v[100:103], v[168:171], v[208:211], v[100:103]
	v_mfma_f32_16x16x32_bf16 v[96:99], v[192:195], v[208:211], v[96:99]
	v_mfma_f32_16x16x32_bf16 v[84:87], v[168:171], v[216:219], v[84:87]
	v_mfma_f32_16x16x32_bf16 v[80:83], v[192:195], v[216:219], v[80:83]
	v_mfma_f32_16x16x32_bf16 v[68:71], v[168:171], v[224:227], v[68:71]
	v_mfma_f32_16x16x32_bf16 v[64:67], v[192:195], v[224:227], v[64:67]
	s_barrier
; #define PG8_STAGE(bufoff, gbase, voff) do { _Pragma("unroll") for (int _i = 0; _i < 2; ++_i) \
;         __builtin_amdgcn_global_load_lds((const unsigned*)((const char*)(gbase) + (voff)[_i]), (PG8_LAS unsigned*)(lds + (bufoff) + ldsw + _i * 8192), 16, 0, 0); } while (0)
; #define PG8_LDA(dst, b, h) do { _Pragma("unroll") for (int m = 0; m < 4; ++m) _Pragma("unroll") for (int k = 0; k < 2; ++k) dst[m][k] = *(const PG8_LAS bf16x8*)(lds + PG8_SA(b, h) + aoff + m * 2048 + k * 1024); } while (0)
; #define PG8_MMA(ai, bj, At, Bt) do { __builtin_amdgcn_s_setprio(1); _Pragma("unroll") for (int m = 0; m < 4; ++m) _Pragma("unroll") for (int n = 0; n < 2; ++n) _Pragma("unroll") for (int k = 0; k < 2; ++k) \
;         acc[ai][bj][m][n] = __builtin_amdgcn_mfma_f32_16x16x32_bf16(Bt[n][k], At[m][k], acc[ai][bj][m][n], 0, 0, 0); __builtin_amdgcn_s_setprio(0); } while (0)
; #define PG8_WAIT_V(n) asm volatile("s_waitcnt vmcnt(" #n ")" ::: "memory")
; #define PG8_WAIT_L(n) asm volatile("s_waitcnt lgkmcnt(" #n ")" ::: "memory")
; #define PG8_BAR __builtin_amdgcn_s_barrier()
; #define PG8_SCHED __builtin_amdgcn_sched_barrier(0)
; template <class Epi, class Sched, bool ALIGN_EPI = false, bool SP2 = false>
; __device__ __forceinline__ void gemm_phase(PG8_LAS unsigned char* lds, const Gemm g, const Sched& S, const Epi& E) {
;     ...
;         for (int t = 0; t < nt; t += 2) {
;             const bool last = (t == nt - 2);
;             const char* a1 = cA + (size_t)(t + 1) * kstep;
;             const char* a2 = last ? nA : cA + (size_t)(t + 2) * kstep; const char* b2 = last ? nB : cB + (size_t)(t + 2) * kstep;
;             const char* a3 = a2 + kstep; const char* b3 = b2 + kstep;
;     ...
;             PG8_WAIT_V(8); PG8_WAIT_L(0); PG8_BAR; PG8_MMA(0, 0, At, B0); PG8_MMA(0, 1, At, B1); PG8_BAR; PG8_SCHED;
;             PG8_LDA(At, 1, 1); PG8_STAGE(PG8_SB(1, 0), b3, voffB); PG8_STAGE(PG8_SB(1, 1), b3 + hstep, voffB); PG8_STAGE(PG8_SA(1, 0), a3, voffA);
;             PG8_WAIT_V(8); PG8_WAIT_L(0); PG8_BAR; PG8_MMA(1, 0, At, B0); PG8_MMA(1, 1, At, B1); PG8_BAR; PG8_SCHED;
	s_setprio 0
	s_add_i32 s46, s93, s63
	v_lshl_add_u64 v[146:147], v[146:147], 0, s[18:19]
	s_mov_b32 m0, s46
	ds_read_b128 v[196:199], v151 offset:49152
	ds_read_b128 v[200:203], v151 offset:50176
	ds_read_b128 v[204:207], v151 offset:51200
	ds_read_b128 v[208:211], v151 offset:52224
	ds_read_b128 v[212:215], v151 offset:53248
	ds_read_b128 v[216:219], v151 offset:54272
	ds_read_b128 v[220:223], v151 offset:55296
	ds_read_b128 v[224:227], v151 offset:56320
	global_load_lds_dwordx4 v[146:147], off
	v_lshl_add_u64 v[146:147], v[182:183], 0, s[18:19]
	s_add_i32 m0, s46, 0x2000
	s_add_i32 s46, s68, s63
	global_load_lds_dwordx4 v[146:147], off
	v_lshl_add_u64 v[146:147], v[184:185], 0, s[18:19]
	s_mov_b32 m0, s46
	s_nop 0
	global_load_lds_dwordx4 v[146:147], off
	v_lshl_add_u64 v[146:147], v[188:189], 0, s[18:19]
	s_add_i32 m0, s46, 0x2000
	s_nop 0
	global_load_lds_dwordx4 v[146:147], off
	v_lshl_add_u64 v[146:147], v[190:191], 0, s[18:19]
	s_mov_b32 m0, s0
	s_nop 0
	global_load_lds_dwordx4 v[146:147], off
	v_lshl_add_u64 v[146:147], v[228:229], 0, s[18:19]
	s_mov_b32 m0, s58
	s_nop 0
	global_load_lds_dwordx4 v[146:147], off
	s_waitcnt vmcnt(8)
	s_waitcnt lgkmcnt(0)
	s_setprio 1
	s_barrier
	v_mfma_f32_16x16x32_bf16 v[60:63], v[138:141], v[196:199], v[60:63]
	v_mfma_f32_16x16x32_bf16 v[56:59], v[156:159], v[196:199], v[56:59]
	v_mfma_f32_16x16x32_bf16 v[44:47], v[138:141], v[204:207], v[44:47]
	v_mfma_f32_16x16x32_bf16 v[40:43], v[156:159], v[204:207], v[40:43]
	v_mfma_f32_16x16x32_bf16 v[28:31], v[138:141], v[212:215], v[28:31]
	v_mfma_f32_16x16x32_bf16 v[24:27], v[156:159], v[212:215], v[24:27]
	v_mfma_f32_16x16x32_bf16 v[12:15], v[138:141], v[220:223], v[12:15]
	v_mfma_f32_16x16x32_bf16 v[8:11], v[156:159], v[220:223], v[8:11]
	v_mfma_f32_16x16x32_bf16 v[60:63], v[142:145], v[200:203], v[60:63]
	v_mfma_f32_16x16x32_bf16 v[56:59], v[160:163], v[200:203], v[56:59]
	v_mfma_f32_16x16x32_bf16 v[44:47], v[142:145], v[208:211], v[44:47]
	v_mfma_f32_16x16x32_bf16 v[40:43], v[160:163], v[208:211], v[40:43]
	v_mfma_f32_16x16x32_bf16 v[28:31], v[142:145], v[216:219], v[28:31]
	v_mfma_f32_16x16x32_bf16 v[24:27], v[160:163], v[216:219], v[24:27]
	v_mfma_f32_16x16x32_bf16 v[12:15], v[142:145], v[224:227], v[12:15]
	v_mfma_f32_16x16x32_bf16 v[8:11], v[160:163], v[224:227], v[8:11]
	v_mfma_f32_16x16x32_bf16 v[52:55], v[164:167], v[196:199], v[52:55]
	v_mfma_f32_16x16x32_bf16 v[48:51], v[172:175], v[196:199], v[48:51]
	v_mfma_f32_16x16x32_bf16 v[36:39], v[164:167], v[204:207], v[36:39]
	v_mfma_f32_16x16x32_bf16 v[32:35], v[172:175], v[204:207], v[32:35]
	v_mfma_f32_16x16x32_bf16 v[20:23], v[164:167], v[212:215], v[20:23]
	v_mfma_f32_16x16x32_bf16 v[16:19], v[172:175], v[212:215], v[16:19]
	v_mfma_f32_16x16x32_bf16 v[4:7], v[164:167], v[220:223], v[4:7]
	v_mfma_f32_16x16x32_bf16 v[0:3], v[172:175], v[220:223], v[0:3]
	v_mfma_f32_16x16x32_bf16 v[52:55], v[168:171], v[200:203], v[52:55]
	v_mfma_f32_16x16x32_bf16 v[48:51], v[192:195], v[200:203], v[48:51]
	v_mfma_f32_16x16x32_bf16 v[36:39], v[168:171], v[208:211], v[36:39]
	v_mfma_f32_16x16x32_bf16 v[32:35], v[192:195], v[208:211], v[32:35]
	v_mfma_f32_16x16x32_bf16 v[20:23], v[168:171], v[216:219], v[20:23]
	v_mfma_f32_16x16x32_bf16 v[16:19], v[192:195], v[216:219], v[16:19]
	v_mfma_f32_16x16x32_bf16 v[4:7], v[168:171], v[224:227], v[4:7]
	v_mfma_f32_16x16x32_bf16 v[0:3], v[192:195], v[224:227], v[0:3]
	s_barrier
	s_setprio 0
	s_add_u32 s44, s44, 0x100
	s_addc_u32 s45, s45, 0
	s_add_u32 s86, s86, 0x100
	s_addc_u32 s87, s87, 0
	s_cmp_ge_u32 vcc_lo, s14
	s_mov_b32 s46, vcc_lo
	s_cbranch_scc0 .LBB0_218
	s_and_b64 vcc, exec, s[36:37]
	s_cbranch_vccz .LBB0_221
	s_barrier

; #define PG8_STAGE(bufoff, gbase, voff) do { _Pragma("unroll") for (int _i = 0; _i < 2; ++_i) \
;         __builtin_amdgcn_global_load_lds((const unsigned*)((const char*)(gbase) + (voff)[_i]), (PG8_LAS unsigned*)(lds + (bufoff) + ldsw + _i * 8192), 16, 0, 0); } while (0)
; #define PG8_LDA(dst, b, h) do { _Pragma("unroll") for (int m = 0; m < 4; ++m) _Pragma("unroll") for (int k = 0; k < 2; ++k) dst[m][k] = *(const PG8_LAS bf16x8*)(lds + PG8_SA(b, h) + aoff + m * 2048 + k * 1024); } while (0)
; #define PG8_LDB(dst, b, h) do { _Pragma("unroll") for (int n = 0; n < 2; ++n) _Pragma("unroll") for (int k = 0; k < 2; ++k) dst[n][k] = *(const PG8_LAS bf16x8*)(lds + PG8_SB(b, h) + boff + n * 2048 + k * 1024); } while (0)
; #define PG8_MMA(ai, bj, At, Bt) do { __builtin_amdgcn_s_setprio(1); _Pragma("unroll") for (int m = 0; m < 4; ++m) _Pragma("unroll") for (int n = 0; n < 2; ++n) _Pragma("unroll") for (int k = 0; k < 2; ++k) \
;         acc[ai][bj][m][n] = __builtin_amdgcn_mfma_f32_16x16x32_bf16(Bt[n][k], At[m][k], acc[ai][bj][m][n], 0, 0, 0); __builtin_amdgcn_s_setprio(0); } while (0)
; #define PG8_WAIT_V(n) asm volatile("s_waitcnt vmcnt(" #n ")" ::: "memory")
; #define PG8_WAIT_L(n) asm volatile("s_waitcnt lgkmcnt(" #n ")" ::: "memory")
; #define PG8_BAR __builtin_amdgcn_s_barrier()
; #define PG8_SCHED __builtin_amdgcn_sched_barrier(0)
; template <class Epi, class Sched, bool ALIGN_EPI = false, bool SP2 = false>
; __device__ __forceinline__ void gemm_phase(PG8_LAS unsigned char* lds, const Gemm g, const Sched& S, const Epi& E) {
;     ...
;             const bool last = (t == nt - 2);
;             const char* a1 = cA + (size_t)(t + 1) * kstep;
;             const char* a2 = last ? nA : cA + (size_t)(t + 2) * kstep; const char* b2 = last ? nB : cB + (size_t)(t + 2) * kstep;
;             const char* a3 = a2 + kstep; const char* b3 = b2 + kstep;
;             if (last && has_next) S.a_ready(nxt);
;             if constexpr (SP2) {
;             PG8_LDB(B0, 0, 0); PG8_LDB(B1, 0, 1); PG8_SCHED; PG8_LDA(At, 0, 0); PG8_STAGE(PG8_SA(1, 1), a1 + hstep, voffA);
;             PG8_WAIT_V(8); PG8_WAIT_L(0); PG8_BAR; PG8_MMA(0, 0, At, B0); PG8_MMA(0, 1, At, B1); PG8_BAR; PG8_SCHED;
;             PG8_LDA(At, 0, 1); PG8_STAGE(PG8_SB(0, 0), b2, voffB); PG8_STAGE(PG8_SB(0, 1), b2 + hstep, voffB); PG8_STAGE(PG8_SA(0, 0), a2, voffA);
.LBB0_331:
	s_add_u32 s68, s74, 0xfff80080
	s_addc_u32 s69, s75, -1
	s_add_i32 s82, 0, 0x10000
	s_cmp_eq_u32 s81, 28
	s_cselect_b32 s79, s45, s69
	s_cselect_b32 s78, s59, s68
	v_add_u32_e32 v140, s82, v143
	s_cselect_b32 s77, s43, s80
	s_cselect_b32 s76, s63, s71
	s_add_i32 s68, 0, 0x14000
	ds_read_b128 v[146:149], v140
	ds_read_b128 v[156:159], v140 offset:1024
	ds_read_b128 v[160:163], v140 offset:2048
	ds_read_b128 v[164:167], v140 offset:3072
	v_add_u32_e32 v140, s68, v143
	ds_read_b128 v[168:171], v140
	ds_read_b128 v[172:175], v140 offset:1024
	ds_read_b128 v[192:195], v140 offset:2048
	ds_read_b128 v[196:199], v140 offset:3072
	v_lshl_add_u64 v[140:141], s[74:75], 0, v[136:137]
	s_add_i32 m0, s16, 0xc000
	ds_read_b128 v[200:203], v145
	ds_read_b128 v[204:207], v145 offset:1024
	ds_read_b128 v[208:211], v145 offset:2048
	ds_read_b128 v[212:215], v145 offset:3072
	ds_read_b128 v[216:219], v145 offset:4096
	ds_read_b128 v[220:223], v145 offset:5120
	ds_read_b128 v[224:227], v145 offset:6144
	ds_read_b128 v[228:231], v145 offset:7168
	global_load_lds_dwordx4 v[140:141], off
	v_lshl_add_u64 v[140:141], s[74:75], 0, v[138:139]
	s_add_i32 m0, s16, 0xe000
	s_nop 0
	global_load_lds_dwordx4 v[140:141], off
	s_waitcnt vmcnt(8)
	s_waitcnt lgkmcnt(0)
	s_setprio 1
	s_barrier
	v_mfma_f32_16x16x32_bf16 v[116:119], v[146:149], v[200:203], v[116:119]
	v_mfma_f32_16x16x32_bf16 v[112:115], v[160:163], v[200:203], v[112:115]
	v_mfma_f32_16x16x32_bf16 v[104:107], v[146:149], v[208:211], v[104:107]
	v_mfma_f32_16x16x32_bf16 v[96:99], v[160:163], v[208:211], v[96:99]
	v_mfma_f32_16x16x32_bf16 v[88:91], v[146:149], v[216:219], v[88:91]
	v_mfma_f32_16x16x32_bf16 v[80:83], v[160:163], v[216:219], v[80:83]
	v_mfma_f32_16x16x32_bf16 v[72:75], v[146:149], v[224:227], v[72:75]
	v_mfma_f32_16x16x32_bf16 v[64:67], v[160:163], v[224:227], v[64:67]
	v_mfma_f32_16x16x32_bf16 v[116:119], v[156:159], v[204:207], v[116:119]
	v_mfma_f32_16x16x32_bf16 v[112:115], v[164:167], v[204:207], v[112:115]
	v_mfma_f32_16x16x32_bf16 v[104:107], v[156:159], v[212:215], v[104:107]
	v_mfma_f32_16x16x32_bf16 v[96:99], v[164:167], v[212:215], v[96:99]
	v_mfma_f32_16x16x32_bf16 v[88:91], v[156:159], v[220:223], v[88:91]
	v_mfma_f32_16x16x32_bf16 v[80:83], v[164:167], v[220:223], v[80:83]
	v_mfma_f32_16x16x32_bf16 v[72:75], v[156:159], v[228:231], v[72:75]
	v_mfma_f32_16x16x32_bf16 v[64:67], v[164:167], v[228:231], v[64:67]
	v_mfma_f32_16x16x32_bf16 v[124:127], v[168:171], v[200:203], v[124:127]
	v_mfma_f32_16x16x32_bf16 v[120:123], v[192:195], v[200:203], v[120:123]
	v_mfma_f32_16x16x32_bf16 v[108:111], v[168:171], v[208:211], v[108:111]
	v_mfma_f32_16x16x32_bf16 v[100:103], v[192:195], v[208:211], v[100:103]
	v_mfma_f32_16x16x32_bf16 v[92:95], v[168:171], v[216:219], v[92:95]
	v_mfma_f32_16x16x32_bf16 v[84:87], v[192:195], v[216:219], v[84:87]
	v_mfma_f32_16x16x32_bf16 v[76:79], v[168:171], v[224:227], v[76:79]
	v_mfma_f32_16x16x32_bf16 v[68:71], v[192:195], v[224:227], v[68:71]
	v_mfma_f32_16x16x32_bf16 v[124:127], v[172:175], v[204:207], v[124:127]
	v_mfma_f32_16x16x32_bf16 v[120:123], v[196:199], v[204:207], v[120:123]
	v_mfma_f32_16x16x32_bf16 v[108:111], v[172:175], v[212:215], v[108:111]
	v_mfma_f32_16x16x32_bf16 v[100:103], v[196:199], v[212:215], v[100:103]
	v_mfma_f32_16x16x32_bf16 v[92:95], v[172:175], v[220:223], v[92:95]
	v_mfma_f32_16x16x32_bf16 v[84:87], v[196:199], v[220:223], v[84:87]
	v_mfma_f32_16x16x32_bf16 v[76:79], v[172:175], v[228:231], v[76:79]
	v_mfma_f32_16x16x32_bf16 v[68:71], v[196:199], v[228:231], v[68:71]
	s_barrier
	s_setprio 0
	s_add_i32 s69, s82, s15
	v_lshl_add_u64 v[140:141], s[76:77], 0, v[152:153]
	s_mov_b32 m0, s69
	ds_read_b128 v[200:203], v145 offset:16384
	ds_read_b128 v[204:207], v145 offset:17408
	ds_read_b128 v[208:211], v145 offset:18432
	ds_read_b128 v[212:215], v145 offset:19456
	ds_read_b128 v[216:219], v145 offset:20480
	ds_read_b128 v[220:223], v145 offset:21504
	ds_read_b128 v[224:227], v145 offset:22528
	ds_read_b128 v[228:231], v145 offset:23552
	global_load_lds_dwordx4 v[140:141], off
	s_add_i32 m0, s69, 0x2000
	s_add_u32 s82, s76, 0x80000
	v_lshl_add_u64 v[150:151], s[76:77], 0, v[128:129]
	s_addc_u32 s83, s77, 0
	s_add_i32 s68, s68, s15
	global_load_lds_dwordx4 v[150:151], off
	v_lshl_add_u64 v[182:183], s[82:83], 0, v[152:153]
	s_mov_b32 m0, s68
	v_lshl_add_u64 v[184:185], s[78:79], 0, v[130:131]
	global_load_lds_dwordx4 v[182:183], off
	v_lshl_add_u64 v[182:183], s[82:83], 0, v[128:129]
	s_add_i32 m0, s68, 0x2000
	s_nop 0
	global_load_lds_dwordx4 v[182:183], off
	v_lshl_add_u64 v[182:183], s[78:79], 0, v[132:133]
	s_mov_b32 m0, s16
	s_nop 0
	global_load_lds_dwordx4 v[182:183], off
	s_mov_b32 m0, s17
	s_nop 0
	global_load_lds_dwordx4 v[184:185], off
	s_waitcnt vmcnt(8)
	s_waitcnt lgkmcnt(0)
	s_setprio 1
	s_barrier
; #define PG8_STAGE(bufoff, gbase, voff) do { _Pragma("unroll") for (int _i = 0; _i < 2; ++_i) \
;         __builtin_amdgcn_global_load_lds((const unsigned*)((const char*)(gbase) + (voff)[_i]), (PG8_LAS unsigned*)(lds + (bufoff) + ldsw + _i * 8192), 16, 0, 0); } while (0)
; #define PG8_LDA(dst, b, h) do { _Pragma("unroll") for (int m = 0; m < 4; ++m) _Pragma("unroll") for (int k = 0; k < 2; ++k) dst[m][k] = *(const PG8_LAS bf16x8*)(lds + PG8_SA(b, h) + aoff + m * 2048 + k * 1024); } while (0)
; #define PG8_LDB(dst, b, h) do { _Pragma("unroll") for (int n = 0; n < 2; ++n) _Pragma("unroll") for (int k = 0; k < 2; ++k) dst[n][k] = *(const PG8_LAS bf16x8*)(lds + PG8_SB(b, h) + boff + n * 2048 + k * 1024); } while (0)
; #define PG8_MMA(ai, bj, At, Bt) do { __builtin_amdgcn_s_setprio(1); _Pragma("unroll") for (int m = 0; m < 4; ++m) _Pragma("unroll") for (int n = 0; n < 2; ++n) _Pragma("unroll") for (int k = 0; k < 2; ++k) \
;         acc[ai][bj][m][n] = __builtin_amdgcn_mfma_f32_16x16x32_bf16(Bt[n][k], At[m][k], acc[ai][bj][m][n], 0, 0, 0); __builtin_amdgcn_s_setprio(0); } while (0)
; #define PG8_WAIT_V(n) asm volatile("s_waitcnt vmcnt(" #n ")" ::: "memory")
; #define PG8_WAIT_L(n) asm volatile("s_waitcnt lgkmcnt(" #n ")" ::: "memory")
; #define PG8_BAR __builtin_amdgcn_s_barrier()
; #define PG8_SCHED __builtin_amdgcn_sched_barrier(0)
; template <class Epi, class Sched, bool ALIGN_EPI = false, bool SP2 = false>
; __device__ __forceinline__ void gemm_phase(PG8_LAS unsigned char* lds, const Gemm g, const Sched& S, const Epi& E) {
;     ...
;             PG8_WAIT_V(8); PG8_WAIT_L(0); PG8_BAR; PG8_MMA(1, 0, At, B0); PG8_MMA(1, 1, At, B1); PG8_BAR; PG8_SCHED;
;             PG8_LDB(B0, 1, 0); PG8_LDB(B1, 1, 1); PG8_SCHED; PG8_LDA(At, 1, 0); PG8_STAGE(PG8_SA(0, 1), a2 + hstep, voffA);
;             PG8_WAIT_V(8); PG8_WAIT_L(0); PG8_BAR; PG8_MMA(0, 0, At, B0); PG8_MMA(0, 1, At, B1); PG8_BAR; PG8_SCHED;
	v_mfma_f32_16x16x32_bf16 v[56:59], v[146:149], v[200:203], v[56:59]
	v_mfma_f32_16x16x32_bf16 v[48:51], v[160:163], v[200:203], v[48:51]
	v_mfma_f32_16x16x32_bf16 v[40:43], v[146:149], v[208:211], v[40:43]
	v_mfma_f32_16x16x32_bf16 v[32:35], v[160:163], v[208:211], v[32:35]
	v_mfma_f32_16x16x32_bf16 v[24:27], v[146:149], v[216:219], v[24:27]
	v_mfma_f32_16x16x32_bf16 v[16:19], v[160:163], v[216:219], v[16:19]
	v_mfma_f32_16x16x32_bf16 v[8:11], v[146:149], v[224:227], v[8:11]
	v_mfma_f32_16x16x32_bf16 v[4:7], v[160:163], v[224:227], v[4:7]
	v_mfma_f32_16x16x32_bf16 v[56:59], v[156:159], v[204:207], v[56:59]
	v_mfma_f32_16x16x32_bf16 v[48:51], v[164:167], v[204:207], v[48:51]
	v_mfma_f32_16x16x32_bf16 v[40:43], v[156:159], v[212:215], v[40:43]
	v_mfma_f32_16x16x32_bf16 v[32:35], v[164:167], v[212:215], v[32:35]
	v_mfma_f32_16x16x32_bf16 v[24:27], v[156:159], v[220:223], v[24:27]
	v_mfma_f32_16x16x32_bf16 v[16:19], v[164:167], v[220:223], v[16:19]
	v_mfma_f32_16x16x32_bf16 v[8:11], v[156:159], v[228:231], v[8:11]
	v_mfma_f32_16x16x32_bf16 v[4:7], v[164:167], v[228:231], v[4:7]
	v_mfma_f32_16x16x32_bf16 v[60:63], v[168:171], v[200:203], v[60:63]
	v_mfma_f32_16x16x32_bf16 v[52:55], v[192:195], v[200:203], v[52:55]
	v_mfma_f32_16x16x32_bf16 v[44:47], v[168:171], v[208:211], v[44:47]
	v_mfma_f32_16x16x32_bf16 v[36:39], v[192:195], v[208:211], v[36:39]
	v_mfma_f32_16x16x32_bf16 v[28:31], v[168:171], v[216:219], v[28:31]
	v_mfma_f32_16x16x32_bf16 v[20:23], v[192:195], v[216:219], v[20:23]
	v_mfma_f32_16x16x32_bf16 v[12:15], v[168:171], v[224:227], v[12:15]
	v_mfma_f32_16x16x32_bf16 v[0:3], v[192:195], v[224:227], v[0:3]
	v_mfma_f32_16x16x32_bf16 v[60:63], v[172:175], v[204:207], v[60:63]
	v_mfma_f32_16x16x32_bf16 v[52:55], v[196:199], v[204:207], v[52:55]
	v_mfma_f32_16x16x32_bf16 v[44:47], v[172:175], v[212:215], v[44:47]
	v_mfma_f32_16x16x32_bf16 v[36:39], v[196:199], v[212:215], v[36:39]
	v_mfma_f32_16x16x32_bf16 v[28:31], v[172:175], v[220:223], v[28:31]
	v_mfma_f32_16x16x32_bf16 v[20:23], v[196:199], v[220:223], v[20:23]
	v_mfma_f32_16x16x32_bf16 v[12:15], v[172:175], v[228:231], v[12:15]
	v_mfma_f32_16x16x32_bf16 v[0:3], v[196:199], v[228:231], v[0:3]
	s_barrier
	s_setprio 0
	v_add_u32_e32 v155, s93, v143
	s_add_i32 s68, 0, 0x1c000
	ds_read_b128 v[146:149], v155
	ds_read_b128 v[156:159], v155 offset:1024
	ds_read_b128 v[160:163], v155 offset:2048
	ds_read_b128 v[164:167], v155 offset:3072
	v_add_u32_e32 v155, s68, v143
	ds_read_b128 v[168:171], v155
	ds_read_b128 v[172:175], v155 offset:1024
	ds_read_b128 v[192:195], v155 offset:2048
	ds_read_b128 v[196:199], v155 offset:3072
	s_add_u32 s78, s78, 0x80000
	s_addc_u32 s79, s79, 0
	s_mov_b32 m0, s22
	v_lshl_add_u64 v[188:189], s[78:79], 0, v[132:133]
	ds_read_b128 v[200:203], v145 offset:32768
	ds_read_b128 v[204:207], v145 offset:33792
	ds_read_b128 v[208:211], v145 offset:34816
	ds_read_b128 v[212:215], v145 offset:35840
	ds_read_b128 v[216:219], v145 offset:36864
	ds_read_b128 v[220:223], v145 offset:37888
	ds_read_b128 v[224:227], v145 offset:38912
	ds_read_b128 v[228:231], v145 offset:39936
	global_load_lds_dwordx4 v[188:189], off
	v_lshl_add_u64 v[188:189], s[78:79], 0, v[130:131]
	s_mov_b32 m0, s23
	s_nop 0
	global_load_lds_dwordx4 v[188:189], off
	s_waitcnt vmcnt(8)
	s_waitcnt lgkmcnt(0)
	s_setprio 1
	s_barrier
	v_mfma_f32_16x16x32_bf16 v[116:119], v[146:149], v[200:203], v[116:119]
	v_mfma_f32_16x16x32_bf16 v[112:115], v[160:163], v[200:203], v[112:115]
	v_mfma_f32_16x16x32_bf16 v[104:107], v[146:149], v[208:211], v[104:107]
	v_mfma_f32_16x16x32_bf16 v[96:99], v[160:163], v[208:211], v[96:99]
	v_mfma_f32_16x16x32_bf16 v[88:91], v[146:149], v[216:219], v[88:91]
	v_mfma_f32_16x16x32_bf16 v[80:83], v[160:163], v[216:219], v[80:83]
	v_mfma_f32_16x16x32_bf16 v[72:75], v[146:149], v[224:227], v[72:75]
	v_mfma_f32_16x16x32_bf16 v[64:67], v[160:163], v[224:227], v[64:67]
	v_mfma_f32_16x16x32_bf16 v[116:119], v[156:159], v[204:207], v[116:119]
	v_mfma_f32_16x16x32_bf16 v[112:115], v[164:167], v[204:207], v[112:115]
	v_mfma_f32_16x16x32_bf16 v[104:107], v[156:159], v[212:215], v[104:107]
	v_mfma_f32_16x16x32_bf16 v[96:99], v[164:167], v[212:215], v[96:99]
	v_mfma_f32_16x16x32_bf16 v[88:91], v[156:159], v[220:223], v[88:91]
	v_mfma_f32_16x16x32_bf16 v[80:83], v[164:167], v[220:223], v[80:83]
	v_mfma_f32_16x16x32_bf16 v[72:75], v[156:159], v[228:231], v[72:75]
	v_mfma_f32_16x16x32_bf16 v[64:67], v[164:167], v[228:231], v[64:67]
	v_mfma_f32_16x16x32_bf16 v[124:127], v[168:171], v[200:203], v[124:127]
	v_mfma_f32_16x16x32_bf16 v[120:123], v[192:195], v[200:203], v[120:123]
	v_mfma_f32_16x16x32_bf16 v[108:111], v[168:171], v[208:211], v[108:111]
	v_mfma_f32_16x16x32_bf16 v[100:103], v[192:195], v[208:211], v[100:103]
	v_mfma_f32_16x16x32_bf16 v[92:95], v[168:171], v[216:219], v[92:95]
	v_mfma_f32_16x16x32_bf16 v[84:87], v[192:195], v[216:219], v[84:87]
	v_mfma_f32_16x16x32_bf16 v[76:79], v[168:171], v[224:227], v[76:79]
	v_mfma_f32_16x16x32_bf16 v[68:71], v[192:195], v[224:227], v[68:71]
	v_mfma_f32_16x16x32_bf16 v[124:127], v[172:175], v[204:207], v[124:127]
	v_mfma_f32_16x16x32_bf16 v[120:123], v[196:199], v[204:207], v[120:123]
	v_mfma_f32_16x16x32_bf16 v[108:111], v[172:175], v[212:215], v[108:111]
	v_mfma_f32_16x16x32_bf16 v[100:103], v[196:199], v[212:215], v[100:103]
	v_mfma_f32_16x16x32_bf16 v[92:95], v[172:175], v[220:223], v[92:95]
	v_mfma_f32_16x16x32_bf16 v[84:87], v[196:199], v[220:223], v[84:87]
	v_mfma_f32_16x16x32_bf16 v[76:79], v[172:175], v[228:231], v[76:79]
	v_mfma_f32_16x16x32_bf16 v[68:71], v[196:199], v[228:231], v[68:71]
	s_barrier
; #define PG8_STAGE(bufoff, gbase, voff) do { _Pragma("unroll") for (int _i = 0; _i < 2; ++_i) \
;         __builtin_amdgcn_global_load_lds((const unsigned*)((const char*)(gbase) + (voff)[_i]), (PG8_LAS unsigned*)(lds + (bufoff) + ldsw + _i * 8192), 16, 0, 0); } while (0)
; #define PG8_LDA(dst, b, h) do { _Pragma("unroll") for (int m = 0; m < 4; ++m) _Pragma("unroll") for (int k = 0; k < 2; ++k) dst[m][k] = *(const PG8_LAS bf16x8*)(lds + PG8_SA(b, h) + aoff + m * 2048 + k * 1024); } while (0)
; #define PG8_MMA(ai, bj, At, Bt) do { __builtin_amdgcn_s_setprio(1); _Pragma("unroll") for (int m = 0; m < 4; ++m) _Pragma("unroll") for (int n = 0; n < 2; ++n) _Pragma("unroll") for (int k = 0; k < 2; ++k) \
;         acc[ai][bj][m][n] = __builtin_amdgcn_mfma_f32_16x16x32_bf16(Bt[n][k], At[m][k], acc[ai][bj][m][n], 0, 0, 0); __builtin_amdgcn_s_setprio(0); } while (0)
; #define PG8_WAIT_V(n) asm volatile("s_waitcnt vmcnt(" #n ")" ::: "memory")
; #define PG8_WAIT_L(n) asm volatile("s_waitcnt lgkmcnt(" #n ")" ::: "memory")
; #define PG8_BAR __builtin_amdgcn_s_barrier()
; #define PG8_SCHED __builtin_amdgcn_sched_barrier(0)
; template <class Epi, class Sched, bool ALIGN_EPI = false, bool SP2 = false>
; __device__ __forceinline__ void gemm_phase(PG8_LAS unsigned char* lds, const Gemm g, const Sched& S, const Epi& E) {
;     ...
;         for (int t = 0; t < nt; t += 2) {
;             const bool last = (t == nt - 2);
;             const char* a1 = cA + (size_t)(t + 1) * kstep;
;             const char* a2 = last ? nA : cA + (size_t)(t + 2) * kstep; const char* b2 = last ? nB : cB + (size_t)(t + 2) * kstep;
;             const char* a3 = a2 + kstep; const char* b3 = b2 + kstep;
;     ...
;             PG8_WAIT_V(8); PG8_WAIT_L(0); PG8_BAR; PG8_MMA(0, 0, At, B0); PG8_MMA(0, 1, At, B1); PG8_BAR; PG8_SCHED;
;             PG8_LDA(At, 1, 1); PG8_STAGE(PG8_SB(1, 0), b3, voffB); PG8_STAGE(PG8_SB(1, 1), b3 + hstep, voffB); PG8_STAGE(PG8_SA(1, 0), a3, voffA);
;             PG8_WAIT_V(8); PG8_WAIT_L(0); PG8_BAR; PG8_MMA(1, 0, At, B0); PG8_MMA(1, 1, At, B1); PG8_BAR; PG8_SCHED;
	s_setprio 0
	s_add_i32 s69, s93, s15
	v_lshl_add_u64 v[140:141], v[140:141], 0, s[18:19]
	s_mov_b32 m0, s69
	ds_read_b128 v[200:203], v145 offset:49152
	ds_read_b128 v[204:207], v145 offset:50176
	ds_read_b128 v[208:211], v145 offset:51200
	ds_read_b128 v[212:215], v145 offset:52224
	ds_read_b128 v[216:219], v145 offset:53248
	ds_read_b128 v[220:223], v145 offset:54272
	ds_read_b128 v[224:227], v145 offset:55296
	ds_read_b128 v[228:231], v145 offset:56320
	global_load_lds_dwordx4 v[140:141], off
	s_add_i32 m0, s69, 0x2000
	s_add_u32 s76, s76, 0x80080
	v_lshl_add_u64 v[140:141], v[150:151], 0, s[18:19]
	s_addc_u32 s77, s77, 0
	s_add_i32 s68, s68, s15
	global_load_lds_dwordx4 v[140:141], off
	v_lshl_add_u64 v[140:141], s[76:77], 0, v[152:153]
	s_mov_b32 m0, s68
	s_nop 0
	global_load_lds_dwordx4 v[140:141], off
	v_lshl_add_u64 v[140:141], s[76:77], 0, v[128:129]
	s_add_i32 m0, s68, 0x2000
	s_nop 0
	global_load_lds_dwordx4 v[140:141], off
	v_lshl_add_u64 v[140:141], v[182:183], 0, s[18:19]
	s_mov_b32 m0, s26
	s_nop 0
	global_load_lds_dwordx4 v[140:141], off
	v_lshl_add_u64 v[140:141], v[184:185], 0, s[18:19]
	s_mov_b32 m0, s34
	s_nop 0
	global_load_lds_dwordx4 v[140:141], off
	s_waitcnt vmcnt(8)
	s_waitcnt lgkmcnt(0)
	s_setprio 1
	s_barrier
	v_mfma_f32_16x16x32_bf16 v[56:59], v[146:149], v[200:203], v[56:59]
	v_mfma_f32_16x16x32_bf16 v[48:51], v[160:163], v[200:203], v[48:51]
	v_mfma_f32_16x16x32_bf16 v[40:43], v[146:149], v[208:211], v[40:43]
	v_mfma_f32_16x16x32_bf16 v[32:35], v[160:163], v[208:211], v[32:35]
	v_mfma_f32_16x16x32_bf16 v[24:27], v[146:149], v[216:219], v[24:27]
	v_mfma_f32_16x16x32_bf16 v[16:19], v[160:163], v[216:219], v[16:19]
	v_mfma_f32_16x16x32_bf16 v[8:11], v[146:149], v[224:227], v[8:11]
	v_mfma_f32_16x16x32_bf16 v[4:7], v[160:163], v[224:227], v[4:7]
	v_mfma_f32_16x16x32_bf16 v[56:59], v[156:159], v[204:207], v[56:59]
	v_mfma_f32_16x16x32_bf16 v[48:51], v[164:167], v[204:207], v[48:51]
	v_mfma_f32_16x16x32_bf16 v[40:43], v[156:159], v[212:215], v[40:43]
	v_mfma_f32_16x16x32_bf16 v[32:35], v[164:167], v[212:215], v[32:35]
	v_mfma_f32_16x16x32_bf16 v[24:27], v[156:159], v[220:223], v[24:27]
	v_mfma_f32_16x16x32_bf16 v[16:19], v[164:167], v[220:223], v[16:19]
	v_mfma_f32_16x16x32_bf16 v[8:11], v[156:159], v[228:231], v[8:11]
	v_mfma_f32_16x16x32_bf16 v[4:7], v[164:167], v[228:231], v[4:7]
	v_mfma_f32_16x16x32_bf16 v[60:63], v[168:171], v[200:203], v[60:63]
	v_mfma_f32_16x16x32_bf16 v[52:55], v[192:195], v[200:203], v[52:55]
	v_mfma_f32_16x16x32_bf16 v[44:47], v[168:171], v[208:211], v[44:47]
	v_mfma_f32_16x16x32_bf16 v[36:39], v[192:195], v[208:211], v[36:39]
	v_mfma_f32_16x16x32_bf16 v[28:31], v[168:171], v[216:219], v[28:31]
	v_mfma_f32_16x16x32_bf16 v[20:23], v[192:195], v[216:219], v[20:23]
	v_mfma_f32_16x16x32_bf16 v[12:15], v[168:171], v[224:227], v[12:15]
	v_mfma_f32_16x16x32_bf16 v[0:3], v[192:195], v[224:227], v[0:3]
	v_mfma_f32_16x16x32_bf16 v[60:63], v[172:175], v[204:207], v[60:63]
	v_mfma_f32_16x16x32_bf16 v[52:55], v[196:199], v[204:207], v[52:55]
	v_mfma_f32_16x16x32_bf16 v[44:47], v[172:175], v[212:215], v[44:47]
	v_mfma_f32_16x16x32_bf16 v[36:39], v[196:199], v[212:215], v[36:39]
	v_mfma_f32_16x16x32_bf16 v[28:31], v[172:175], v[220:223], v[28:31]
	v_mfma_f32_16x16x32_bf16 v[20:23], v[196:199], v[220:223], v[20:23]
	v_mfma_f32_16x16x32_bf16 v[12:15], v[172:175], v[228:231], v[12:15]
	v_mfma_f32_16x16x32_bf16 v[0:3], v[196:199], v[228:231], v[0:3]
	s_barrier
	s_setprio 0
	s_add_i32 s81, s81, 2
	s_add_u32 s74, s74, 0x100
	s_addc_u32 s75, s75, 0
	s_add_u32 s71, s71, 0x100
	s_addc_u32 s80, s80, 0
	s_cmp_gt_u32 s81, 29
	s_cbranch_scc0 .LBB0_331
	s_and_b64 vcc, exec, s[36:37]
	s_cbranch_vccz .LBB0_334
	s_barrier

; #define PG8_STAGE(bufoff, gbase, voff) do { _Pragma("unroll") for (int _i = 0; _i < 2; ++_i) \
;         __builtin_amdgcn_global_load_lds((const unsigned*)((const char*)(gbase) + (voff)[_i]), (PG8_LAS unsigned*)(lds + (bufoff) + ldsw + _i * 8192), 16, 0, 0); } while (0)
; #define PG8_LDA(dst, b, h) do { _Pragma("unroll") for (int m = 0; m < 4; ++m) _Pragma("unroll") for (int k = 0; k < 2; ++k) dst[m][k] = *(const PG8_LAS bf16x8*)(lds + PG8_SA(b, h) + aoff + m * 2048 + k * 1024); } while (0)
; #define PG8_LDB(dst, b, h) do { _Pragma("unroll") for (int n = 0; n < 2; ++n) _Pragma("unroll") for (int k = 0; k < 2; ++k) dst[n][k] = *(const PG8_LAS bf16x8*)(lds + PG8_SB(b, h) + boff + n * 2048 + k * 1024); } while (0)
; #define PG8_MMA(ai, bj, At, Bt) do { __builtin_amdgcn_s_setprio(1); _Pragma("unroll") for (int m = 0; m < 4; ++m) _Pragma("unroll") for (int n = 0; n < 2; ++n) _Pragma("unroll") for (int k = 0; k < 2; ++k) \
;         acc[ai][bj][m][n] = __builtin_amdgcn_mfma_f32_16x16x32_bf16(Bt[n][k], At[m][k], acc[ai][bj][m][n], 0, 0, 0); __builtin_amdgcn_s_setprio(0); } while (0)
; #define PG8_WAIT_V(n) asm volatile("s_waitcnt vmcnt(" #n ")" ::: "memory")
; #define PG8_WAIT_L(n) asm volatile("s_waitcnt lgkmcnt(" #n ")" ::: "memory")
; #define PG8_BAR __builtin_amdgcn_s_barrier()
; #define PG8_SCHED __builtin_amdgcn_sched_barrier(0)
; template <class Epi, class Sched, bool ALIGN_EPI = false, bool SP2 = false>
; __device__ __forceinline__ void gemm_phase(PG8_LAS unsigned char* lds, const Gemm g, const Sched& S, const Epi& E) {
;     ...
;             const bool last = (t == nt - 2);
;             const char* a1 = cA + (size_t)(t + 1) * kstep;
;             const char* a2 = last ? nA : cA + (size_t)(t + 2) * kstep; const char* b2 = last ? nB : cB + (size_t)(t + 2) * kstep;
;             const char* a3 = a2 + kstep; const char* b3 = b2 + kstep;
;             if (last && has_next) S.a_ready(nxt);
;             if constexpr (SP2) {
;             PG8_LDB(B0, 0, 0); PG8_LDB(B1, 0, 1); PG8_SCHED; PG8_LDA(At, 0, 0); PG8_STAGE(PG8_SA(1, 1), a1 + hstep, voffA);
;             PG8_WAIT_V(8); PG8_WAIT_L(0); PG8_BAR; PG8_MMA(0, 0, At, B0); PG8_MMA(0, 1, At, B1); PG8_BAR; PG8_SCHED;
;             PG8_LDA(At, 0, 1); PG8_STAGE(PG8_SB(0, 0), b2, voffB); PG8_STAGE(PG8_SB(0, 1), b2 + hstep, voffB); PG8_STAGE(PG8_SA(0, 0), a2, voffA);
.LBB0_354:
	s_add_u32 s68, s48, 0xfff80080
	s_addc_u32 s69, s49, -1
	s_add_i32 s78, 0, 0x10000
	s_cmp_eq_u32 s71, 28
	s_cselect_b32 s77, s41, s69
	s_cselect_b32 s76, s55, s68
	v_add_u32_e32 v150, s78, v139
	s_cselect_b32 s75, s39, s63
	s_cselect_b32 s74, s58, s59
	s_add_i32 s68, 0, 0x14000
	ds_read_b128 v[142:145], v150
	ds_read_b128 v[146:149], v150 offset:1024
	ds_read_b128 v[156:159], v150 offset:2048
	ds_read_b128 v[160:163], v150 offset:3072
	v_add_u32_e32 v150, s68, v139
	ds_read_b128 v[164:167], v150
	ds_read_b128 v[168:171], v150 offset:1024
	ds_read_b128 v[172:175], v150 offset:2048
	ds_read_b128 v[192:195], v150 offset:3072
	v_lshl_add_u64 v[150:151], s[48:49], 0, v[134:135]
	s_add_i32 m0, s16, 0xc000
	ds_read_b128 v[196:199], v141
	ds_read_b128 v[200:203], v141 offset:1024
	ds_read_b128 v[204:207], v141 offset:2048
	ds_read_b128 v[208:211], v141 offset:3072
	ds_read_b128 v[212:215], v141 offset:4096
	ds_read_b128 v[216:219], v141 offset:5120
	ds_read_b128 v[220:223], v141 offset:6144
	ds_read_b128 v[224:227], v141 offset:7168
	global_load_lds_dwordx4 v[150:151], off
	v_lshl_add_u64 v[150:151], s[48:49], 0, v[136:137]
	s_add_i32 m0, s16, 0xe000
	s_nop 0
	global_load_lds_dwordx4 v[150:151], off
	s_waitcnt vmcnt(8)
	s_waitcnt lgkmcnt(0)
	s_setprio 1
	s_barrier
	v_mfma_f32_16x16x32_bf16 v[124:127], v[142:145], v[196:199], v[124:127]
	v_mfma_f32_16x16x32_bf16 v[120:123], v[156:159], v[196:199], v[120:123]
	v_mfma_f32_16x16x32_bf16 v[116:119], v[142:145], v[204:207], v[116:119]
	v_mfma_f32_16x16x32_bf16 v[108:111], v[156:159], v[204:207], v[108:111]
	v_mfma_f32_16x16x32_bf16 v[100:103], v[142:145], v[212:215], v[100:103]
	v_mfma_f32_16x16x32_bf16 v[92:95], v[156:159], v[212:215], v[92:95]
	v_mfma_f32_16x16x32_bf16 v[84:87], v[142:145], v[220:223], v[84:87]
	v_mfma_f32_16x16x32_bf16 v[76:79], v[156:159], v[220:223], v[76:79]
	v_mfma_f32_16x16x32_bf16 v[124:127], v[146:149], v[200:203], v[124:127]
	v_mfma_f32_16x16x32_bf16 v[120:123], v[160:163], v[200:203], v[120:123]
	v_mfma_f32_16x16x32_bf16 v[116:119], v[146:149], v[208:211], v[116:119]
	v_mfma_f32_16x16x32_bf16 v[108:111], v[160:163], v[208:211], v[108:111]
	v_mfma_f32_16x16x32_bf16 v[100:103], v[146:149], v[216:219], v[100:103]
	v_mfma_f32_16x16x32_bf16 v[92:95], v[160:163], v[216:219], v[92:95]
	v_mfma_f32_16x16x32_bf16 v[84:87], v[146:149], v[224:227], v[84:87]
	v_mfma_f32_16x16x32_bf16 v[76:79], v[160:163], v[224:227], v[76:79]
	v_mfma_f32_16x16x32_bf16 v[112:115], v[164:167], v[196:199], v[112:115]
	v_mfma_f32_16x16x32_bf16 v[104:107], v[172:175], v[196:199], v[104:107]
	v_mfma_f32_16x16x32_bf16 v[96:99], v[164:167], v[204:207], v[96:99]
	v_mfma_f32_16x16x32_bf16 v[88:91], v[172:175], v[204:207], v[88:91]
	v_mfma_f32_16x16x32_bf16 v[80:83], v[164:167], v[212:215], v[80:83]
	v_mfma_f32_16x16x32_bf16 v[72:75], v[172:175], v[212:215], v[72:75]
	v_mfma_f32_16x16x32_bf16 v[68:71], v[164:167], v[220:223], v[68:71]
	v_mfma_f32_16x16x32_bf16 v[64:67], v[172:175], v[220:223], v[64:67]
	v_mfma_f32_16x16x32_bf16 v[112:115], v[168:171], v[200:203], v[112:115]
	v_mfma_f32_16x16x32_bf16 v[104:107], v[192:195], v[200:203], v[104:107]
	v_mfma_f32_16x16x32_bf16 v[96:99], v[168:171], v[208:211], v[96:99]
	v_mfma_f32_16x16x32_bf16 v[88:91], v[192:195], v[208:211], v[88:91]
	v_mfma_f32_16x16x32_bf16 v[80:83], v[168:171], v[216:219], v[80:83]
	v_mfma_f32_16x16x32_bf16 v[72:75], v[192:195], v[216:219], v[72:75]
	v_mfma_f32_16x16x32_bf16 v[68:71], v[168:171], v[224:227], v[68:71]
	v_mfma_f32_16x16x32_bf16 v[64:67], v[192:195], v[224:227], v[64:67]
	s_barrier
	s_setprio 0
	s_add_i32 s69, s78, s0
	v_lshl_add_u64 v[150:151], s[74:75], 0, v[152:153]
	s_mov_b32 m0, s69
	ds_read_b128 v[196:199], v141 offset:16384
	ds_read_b128 v[200:203], v141 offset:17408
	ds_read_b128 v[204:207], v141 offset:18432
	ds_read_b128 v[208:211], v141 offset:19456
	ds_read_b128 v[212:215], v141 offset:20480
	ds_read_b128 v[216:219], v141 offset:21504
	ds_read_b128 v[220:223], v141 offset:22528
	ds_read_b128 v[224:227], v141 offset:23552
	global_load_lds_dwordx4 v[150:151], off
	s_add_i32 m0, s69, 0x2000
	s_add_u32 s78, s74, 0x80000
	v_lshl_add_u64 v[182:183], s[74:75], 0, v[132:133]
	s_addc_u32 s79, s75, 0
	s_add_i32 s68, s68, s0
	global_load_lds_dwordx4 v[182:183], off
	v_lshl_add_u64 v[184:185], s[78:79], 0, v[152:153]
	s_mov_b32 m0, s68
	v_lshl_add_u64 v[188:189], s[76:77], 0, v[130:131]
	global_load_lds_dwordx4 v[184:185], off
	v_lshl_add_u64 v[184:185], s[78:79], 0, v[132:133]
	s_add_i32 m0, s68, 0x2000
	s_nop 0
	global_load_lds_dwordx4 v[184:185], off
	v_lshl_add_u64 v[184:185], s[76:77], 0, v[128:129]
	s_mov_b32 m0, s16
	s_nop 0
	global_load_lds_dwordx4 v[184:185], off
	s_mov_b32 m0, s17
	s_nop 0
	global_load_lds_dwordx4 v[188:189], off
	s_waitcnt vmcnt(8)
	s_waitcnt lgkmcnt(0)
	s_setprio 1
	s_barrier
; #define PG8_STAGE(bufoff, gbase, voff) do { _Pragma("unroll") for (int _i = 0; _i < 2; ++_i) \
;         __builtin_amdgcn_global_load_lds((const unsigned*)((const char*)(gbase) + (voff)[_i]), (PG8_LAS unsigned*)(lds + (bufoff) + ldsw + _i * 8192), 16, 0, 0); } while (0)
; #define PG8_LDA(dst, b, h) do { _Pragma("unroll") for (int m = 0; m < 4; ++m) _Pragma("unroll") for (int k = 0; k < 2; ++k) dst[m][k] = *(const PG8_LAS bf16x8*)(lds + PG8_SA(b, h) + aoff + m * 2048 + k * 1024); } while (0)
; #define PG8_LDB(dst, b, h) do { _Pragma("unroll") for (int n = 0; n < 2; ++n) _Pragma("unroll") for (int k = 0; k < 2; ++k) dst[n][k] = *(const PG8_LAS bf16x8*)(lds + PG8_SB(b, h) + boff + n * 2048 + k * 1024); } while (0)
; #define PG8_MMA(ai, bj, At, Bt) do { __builtin_amdgcn_s_setprio(1); _Pragma("unroll") for (int m = 0; m < 4; ++m) _Pragma("unroll") for (int n = 0; n < 2; ++n) _Pragma("unroll") for (int k = 0; k < 2; ++k) \
;         acc[ai][bj][m][n] = __builtin_amdgcn_mfma_f32_16x16x32_bf16(Bt[n][k], At[m][k], acc[ai][bj][m][n], 0, 0, 0); __builtin_amdgcn_s_setprio(0); } while (0)
; #define PG8_WAIT_V(n) asm volatile("s_waitcnt vmcnt(" #n ")" ::: "memory")
; #define PG8_WAIT_L(n) asm volatile("s_waitcnt lgkmcnt(" #n ")" ::: "memory")
; #define PG8_BAR __builtin_amdgcn_s_barrier()
; #define PG8_SCHED __builtin_amdgcn_sched_barrier(0)
; template <class Epi, class Sched, bool ALIGN_EPI = false, bool SP2 = false>
; __device__ __forceinline__ void gemm_phase(PG8_LAS unsigned char* lds, const Gemm g, const Sched& S, const Epi& E) {
;     ...
;             PG8_WAIT_V(8); PG8_WAIT_L(0); PG8_BAR; PG8_MMA(1, 0, At, B0); PG8_MMA(1, 1, At, B1); PG8_BAR; PG8_SCHED;
;             PG8_LDB(B0, 1, 0); PG8_LDB(B1, 1, 1); PG8_SCHED; PG8_LDA(At, 1, 0); PG8_STAGE(PG8_SA(0, 1), a2 + hstep, voffA);
;             PG8_WAIT_V(8); PG8_WAIT_L(0); PG8_BAR; PG8_MMA(0, 0, At, B0); PG8_MMA(0, 1, At, B1); PG8_BAR; PG8_SCHED;
	v_mfma_f32_16x16x32_bf16 v[60:63], v[142:145], v[196:199], v[60:63]
	v_mfma_f32_16x16x32_bf16 v[56:59], v[156:159], v[196:199], v[56:59]
	v_mfma_f32_16x16x32_bf16 v[52:55], v[142:145], v[204:207], v[52:55]
	v_mfma_f32_16x16x32_bf16 v[44:47], v[156:159], v[204:207], v[44:47]
	v_mfma_f32_16x16x32_bf16 v[36:39], v[142:145], v[212:215], v[36:39]
	v_mfma_f32_16x16x32_bf16 v[28:31], v[156:159], v[212:215], v[28:31]
	v_mfma_f32_16x16x32_bf16 v[20:23], v[142:145], v[220:223], v[20:23]
	v_mfma_f32_16x16x32_bf16 v[12:15], v[156:159], v[220:223], v[12:15]
	v_mfma_f32_16x16x32_bf16 v[60:63], v[146:149], v[200:203], v[60:63]
	v_mfma_f32_16x16x32_bf16 v[56:59], v[160:163], v[200:203], v[56:59]
	v_mfma_f32_16x16x32_bf16 v[52:55], v[146:149], v[208:211], v[52:55]
	v_mfma_f32_16x16x32_bf16 v[44:47], v[160:163], v[208:211], v[44:47]
	v_mfma_f32_16x16x32_bf16 v[36:39], v[146:149], v[216:219], v[36:39]
	v_mfma_f32_16x16x32_bf16 v[28:31], v[160:163], v[216:219], v[28:31]
	v_mfma_f32_16x16x32_bf16 v[20:23], v[146:149], v[224:227], v[20:23]
	v_mfma_f32_16x16x32_bf16 v[12:15], v[160:163], v[224:227], v[12:15]
	v_mfma_f32_16x16x32_bf16 v[48:51], v[164:167], v[196:199], v[48:51]
	v_mfma_f32_16x16x32_bf16 v[40:43], v[172:175], v[196:199], v[40:43]
	v_mfma_f32_16x16x32_bf16 v[32:35], v[164:167], v[204:207], v[32:35]
	v_mfma_f32_16x16x32_bf16 v[24:27], v[172:175], v[204:207], v[24:27]
	v_mfma_f32_16x16x32_bf16 v[16:19], v[164:167], v[212:215], v[16:19]
	v_mfma_f32_16x16x32_bf16 v[8:11], v[172:175], v[212:215], v[8:11]
	v_mfma_f32_16x16x32_bf16 v[4:7], v[164:167], v[220:223], v[4:7]
	v_mfma_f32_16x16x32_bf16 v[0:3], v[172:175], v[220:223], v[0:3]
	v_mfma_f32_16x16x32_bf16 v[48:51], v[168:171], v[200:203], v[48:51]
	v_mfma_f32_16x16x32_bf16 v[40:43], v[192:195], v[200:203], v[40:43]
	v_mfma_f32_16x16x32_bf16 v[32:35], v[168:171], v[208:211], v[32:35]
	v_mfma_f32_16x16x32_bf16 v[24:27], v[192:195], v[208:211], v[24:27]
	v_mfma_f32_16x16x32_bf16 v[16:19], v[168:171], v[216:219], v[16:19]
	v_mfma_f32_16x16x32_bf16 v[8:11], v[192:195], v[216:219], v[8:11]
	v_mfma_f32_16x16x32_bf16 v[4:7], v[168:171], v[224:227], v[4:7]
	v_mfma_f32_16x16x32_bf16 v[0:3], v[192:195], v[224:227], v[0:3]
	s_barrier
	s_setprio 0
	v_add_u32_e32 v155, s93, v139
	s_add_i32 s68, 0, 0x1c000
	ds_read_b128 v[142:145], v155
	ds_read_b128 v[146:149], v155 offset:1024
	ds_read_b128 v[156:159], v155 offset:2048
	ds_read_b128 v[160:163], v155 offset:3072
	v_add_u32_e32 v155, s68, v139
	ds_read_b128 v[164:167], v155
	ds_read_b128 v[168:171], v155 offset:1024
	ds_read_b128 v[172:175], v155 offset:2048
	ds_read_b128 v[192:195], v155 offset:3072
	s_add_u32 s76, s76, 0x80000
	s_addc_u32 s77, s77, 0
	s_mov_b32 m0, s22
	v_lshl_add_u64 v[190:191], s[76:77], 0, v[128:129]
	ds_read_b128 v[196:199], v141 offset:32768
	ds_read_b128 v[200:203], v141 offset:33792
	ds_read_b128 v[204:207], v141 offset:34816
	ds_read_b128 v[208:211], v141 offset:35840
	ds_read_b128 v[212:215], v141 offset:36864
	ds_read_b128 v[216:219], v141 offset:37888
	ds_read_b128 v[220:223], v141 offset:38912
	ds_read_b128 v[224:227], v141 offset:39936
	global_load_lds_dwordx4 v[190:191], off
	v_lshl_add_u64 v[190:191], s[76:77], 0, v[130:131]
	s_mov_b32 m0, s23
	s_nop 0
	global_load_lds_dwordx4 v[190:191], off
	s_waitcnt vmcnt(8)
	s_waitcnt lgkmcnt(0)
	s_setprio 1
	s_barrier
	v_mfma_f32_16x16x32_bf16 v[124:127], v[142:145], v[196:199], v[124:127]
	v_mfma_f32_16x16x32_bf16 v[120:123], v[156:159], v[196:199], v[120:123]
	v_mfma_f32_16x16x32_bf16 v[116:119], v[142:145], v[204:207], v[116:119]
	v_mfma_f32_16x16x32_bf16 v[108:111], v[156:159], v[204:207], v[108:111]
	v_mfma_f32_16x16x32_bf16 v[100:103], v[142:145], v[212:215], v[100:103]
	v_mfma_f32_16x16x32_bf16 v[92:95], v[156:159], v[212:215], v[92:95]
	v_mfma_f32_16x16x32_bf16 v[84:87], v[142:145], v[220:223], v[84:87]
	v_mfma_f32_16x16x32_bf16 v[76:79], v[156:159], v[220:223], v[76:79]
	v_mfma_f32_16x16x32_bf16 v[124:127], v[146:149], v[200:203], v[124:127]
	v_mfma_f32_16x16x32_bf16 v[120:123], v[160:163], v[200:203], v[120:123]
	v_mfma_f32_16x16x32_bf16 v[116:119], v[146:149], v[208:211], v[116:119]
	v_mfma_f32_16x16x32_bf16 v[108:111], v[160:163], v[208:211], v[108:111]
	v_mfma_f32_16x16x32_bf16 v[100:103], v[146:149], v[216:219], v[100:103]
	v_mfma_f32_16x16x32_bf16 v[92:95], v[160:163], v[216:219], v[92:95]
	v_mfma_f32_16x16x32_bf16 v[84:87], v[146:149], v[224:227], v[84:87]
	v_mfma_f32_16x16x32_bf16 v[76:79], v[160:163], v[224:227], v[76:79]
	v_mfma_f32_16x16x32_bf16 v[112:115], v[164:167], v[196:199], v[112:115]
	v_mfma_f32_16x16x32_bf16 v[104:107], v[172:175], v[196:199], v[104:107]
	v_mfma_f32_16x16x32_bf16 v[96:99], v[164:167], v[204:207], v[96:99]
	v_mfma_f32_16x16x32_bf16 v[88:91], v[172:175], v[204:207], v[88:91]
	v_mfma_f32_16x16x32_bf16 v[80:83], v[164:167], v[212:215], v[80:83]
	v_mfma_f32_16x16x32_bf16 v[72:75], v[172:175], v[212:215], v[72:75]
	v_mfma_f32_16x16x32_bf16 v[68:71], v[164:167], v[220:223], v[68:71]
	v_mfma_f32_16x16x32_bf16 v[64:67], v[172:175], v[220:223], v[64:67]
	v_mfma_f32_16x16x32_bf16 v[112:115], v[168:171], v[200:203], v[112:115]
	v_mfma_f32_16x16x32_bf16 v[104:107], v[192:195], v[200:203], v[104:107]
	v_mfma_f32_16x16x32_bf16 v[96:99], v[168:171], v[208:211], v[96:99]
	v_mfma_f32_16x16x32_bf16 v[88:91], v[192:195], v[208:211], v[88:91]
	v_mfma_f32_16x16x32_bf16 v[80:83], v[168:171], v[216:219], v[80:83]
	v_mfma_f32_16x16x32_bf16 v[72:75], v[192:195], v[216:219], v[72:75]
	v_mfma_f32_16x16x32_bf16 v[68:71], v[168:171], v[224:227], v[68:71]
	v_mfma_f32_16x16x32_bf16 v[64:67], v[192:195], v[224:227], v[64:67]
	s_barrier
; #define PG8_STAGE(bufoff, gbase, voff) do { _Pragma("unroll") for (int _i = 0; _i < 2; ++_i) \
;         __builtin_amdgcn_global_load_lds((const unsigned*)((const char*)(gbase) + (voff)[_i]), (PG8_LAS unsigned*)(lds + (bufoff) + ldsw + _i * 8192), 16, 0, 0); } while (0)
; #define PG8_LDA(dst, b, h) do { _Pragma("unroll") for (int m = 0; m < 4; ++m) _Pragma("unroll") for (int k = 0; k < 2; ++k) dst[m][k] = *(const PG8_LAS bf16x8*)(lds + PG8_SA(b, h) + aoff + m * 2048 + k * 1024); } while (0)
; #define PG8_MMA(ai, bj, At, Bt) do { __builtin_amdgcn_s_setprio(1); _Pragma("unroll") for (int m = 0; m < 4; ++m) _Pragma("unroll") for (int n = 0; n < 2; ++n) _Pragma("unroll") for (int k = 0; k < 2; ++k) \
;         acc[ai][bj][m][n] = __builtin_amdgcn_mfma_f32_16x16x32_bf16(Bt[n][k], At[m][k], acc[ai][bj][m][n], 0, 0, 0); __builtin_amdgcn_s_setprio(0); } while (0)
; #define PG8_WAIT_V(n) asm volatile("s_waitcnt vmcnt(" #n ")" ::: "memory")
; #define PG8_WAIT_L(n) asm volatile("s_waitcnt lgkmcnt(" #n ")" ::: "memory")
; #define PG8_BAR __builtin_amdgcn_s_barrier()
; #define PG8_SCHED __builtin_amdgcn_sched_barrier(0)
; template <class Epi, class Sched, bool ALIGN_EPI = false, bool SP2 = false>
; __device__ __forceinline__ void gemm_phase(PG8_LAS unsigned char* lds, const Gemm g, const Sched& S, const Epi& E) {
;     ...
;         for (int t = 0; t < nt; t += 2) {
;             const bool last = (t == nt - 2);
;             const char* a1 = cA + (size_t)(t + 1) * kstep;
;             const char* a2 = last ? nA : cA + (size_t)(t + 2) * kstep; const char* b2 = last ? nB : cB + (size_t)(t + 2) * kstep;
;             const char* a3 = a2 + kstep; const char* b3 = b2 + kstep;
;     ...
;             PG8_WAIT_V(8); PG8_WAIT_L(0); PG8_BAR; PG8_MMA(0, 0, At, B0); PG8_MMA(0, 1, At, B1); PG8_BAR; PG8_SCHED;
;             PG8_LDA(At, 1, 1); PG8_STAGE(PG8_SB(1, 0), b3, voffB); PG8_STAGE(PG8_SB(1, 1), b3 + hstep, voffB); PG8_STAGE(PG8_SA(1, 0), a3, voffA);
;             PG8_WAIT_V(8); PG8_WAIT_L(0); PG8_BAR; PG8_MMA(1, 0, At, B0); PG8_MMA(1, 1, At, B1); PG8_BAR; PG8_SCHED;
	s_setprio 0
	s_add_i32 s69, s93, s0
	v_lshl_add_u64 v[150:151], v[150:151], 0, s[18:19]
	s_mov_b32 m0, s69
	ds_read_b128 v[196:199], v141 offset:49152
	ds_read_b128 v[200:203], v141 offset:50176
	ds_read_b128 v[204:207], v141 offset:51200
	ds_read_b128 v[208:211], v141 offset:52224
	ds_read_b128 v[212:215], v141 offset:53248
	ds_read_b128 v[216:219], v141 offset:54272
	ds_read_b128 v[220:223], v141 offset:55296
	ds_read_b128 v[224:227], v141 offset:56320
	global_load_lds_dwordx4 v[150:151], off
	s_add_i32 m0, s69, 0x2000
	s_add_u32 s74, s74, 0x80080
	v_lshl_add_u64 v[150:151], v[182:183], 0, s[18:19]
	s_addc_u32 s75, s75, 0
	s_add_i32 s68, s68, s0
	global_load_lds_dwordx4 v[150:151], off
	v_lshl_add_u64 v[150:151], s[74:75], 0, v[152:153]
	s_mov_b32 m0, s68
	s_nop 0
	global_load_lds_dwordx4 v[150:151], off
	v_lshl_add_u64 v[150:151], s[74:75], 0, v[132:133]
	s_add_i32 m0, s68, 0x2000
	s_nop 0
	global_load_lds_dwordx4 v[150:151], off
	v_lshl_add_u64 v[150:151], v[184:185], 0, s[18:19]
	s_mov_b32 m0, s26
	s_nop 0
	global_load_lds_dwordx4 v[150:151], off
	v_lshl_add_u64 v[150:151], v[188:189], 0, s[18:19]
	s_mov_b32 m0, s34
	s_nop 0
	global_load_lds_dwordx4 v[150:151], off
	s_waitcnt vmcnt(8)
	s_waitcnt lgkmcnt(0)
	s_setprio 1
	s_barrier
	v_mfma_f32_16x16x32_bf16 v[60:63], v[142:145], v[196:199], v[60:63]
	v_mfma_f32_16x16x32_bf16 v[56:59], v[156:159], v[196:199], v[56:59]
	v_mfma_f32_16x16x32_bf16 v[52:55], v[142:145], v[204:207], v[52:55]
	v_mfma_f32_16x16x32_bf16 v[44:47], v[156:159], v[204:207], v[44:47]
	v_mfma_f32_16x16x32_bf16 v[36:39], v[142:145], v[212:215], v[36:39]
	v_mfma_f32_16x16x32_bf16 v[28:31], v[156:159], v[212:215], v[28:31]
	v_mfma_f32_16x16x32_bf16 v[20:23], v[142:145], v[220:223], v[20:23]
	v_mfma_f32_16x16x32_bf16 v[12:15], v[156:159], v[220:223], v[12:15]
	v_mfma_f32_16x16x32_bf16 v[60:63], v[146:149], v[200:203], v[60:63]
	v_mfma_f32_16x16x32_bf16 v[56:59], v[160:163], v[200:203], v[56:59]
	v_mfma_f32_16x16x32_bf16 v[52:55], v[146:149], v[208:211], v[52:55]
	v_mfma_f32_16x16x32_bf16 v[44:47], v[160:163], v[208:211], v[44:47]
	v_mfma_f32_16x16x32_bf16 v[36:39], v[146:149], v[216:219], v[36:39]
	v_mfma_f32_16x16x32_bf16 v[28:31], v[160:163], v[216:219], v[28:31]
	v_mfma_f32_16x16x32_bf16 v[20:23], v[146:149], v[224:227], v[20:23]
	v_mfma_f32_16x16x32_bf16 v[12:15], v[160:163], v[224:227], v[12:15]
	v_mfma_f32_16x16x32_bf16 v[48:51], v[164:167], v[196:199], v[48:51]
	v_mfma_f32_16x16x32_bf16 v[40:43], v[172:175], v[196:199], v[40:43]
	v_mfma_f32_16x16x32_bf16 v[32:35], v[164:167], v[204:207], v[32:35]
	v_mfma_f32_16x16x32_bf16 v[24:27], v[172:175], v[204:207], v[24:27]
	v_mfma_f32_16x16x32_bf16 v[16:19], v[164:167], v[212:215], v[16:19]
	v_mfma_f32_16x16x32_bf16 v[8:11], v[172:175], v[212:215], v[8:11]
	v_mfma_f32_16x16x32_bf16 v[4:7], v[164:167], v[220:223], v[4:7]
	v_mfma_f32_16x16x32_bf16 v[0:3], v[172:175], v[220:223], v[0:3]
	v_mfma_f32_16x16x32_bf16 v[48:51], v[168:171], v[200:203], v[48:51]
	v_mfma_f32_16x16x32_bf16 v[40:43], v[192:195], v[200:203], v[40:43]
	v_mfma_f32_16x16x32_bf16 v[32:35], v[168:171], v[208:211], v[32:35]
	v_mfma_f32_16x16x32_bf16 v[24:27], v[192:195], v[208:211], v[24:27]
	v_mfma_f32_16x16x32_bf16 v[16:19], v[168:171], v[216:219], v[16:19]
	v_mfma_f32_16x16x32_bf16 v[8:11], v[192:195], v[216:219], v[8:11]
	v_mfma_f32_16x16x32_bf16 v[4:7], v[168:171], v[224:227], v[4:7]
	v_mfma_f32_16x16x32_bf16 v[0:3], v[192:195], v[224:227], v[0:3]
	s_barrier
	s_setprio 0
	s_add_i32 s71, s71, 2
	s_add_u32 s48, s48, 0x100
	s_addc_u32 s49, s49, 0
	s_add_u32 s59, s59, 0x100
	s_addc_u32 s63, s63, 0
	s_cmp_gt_u32 s71, 29
	s_cbranch_scc0 .LBB0_354
	s_and_b64 vcc, exec, s[28:29]
	s_movk_i32 s58, 0x5fe
	s_movk_i32 s59, 0x1810
	s_cbranch_vccz .LBB0_357
	s_barrier
